# all seven GEMM mainloops: LDS-DMA with SGPR base + VGPR offset (no per-load 64-bit VALU add)
# speedup vs baseline: 1.0091x; 1.0014x over previous
; #define PG8_STAGE(bufoff, gbase, voff) do { _Pragma("unroll") for (int _i = 0; _i < 2; ++_i) \
;         __builtin_amdgcn_global_load_lds((const unsigned*)((const char*)(gbase) + (voff)[_i]), (LAS unsigned*)(lds + (bufoff) + ldsw + _i * 8192), 16, 0, 0); } while (0)
; #define PG8_LDA(dst, b, h) do { _Pragma("unroll") for (int m = 0; m < 4; ++m) _Pragma("unroll") for (int k = 0; k < 2; ++k) dst[m][k] = *(const LAS bf16x8*)(lds + PG8_SA(b, h) + aoff + m * 2048 + k * 1024); } while (0)
; #define PG8_LDB(dst, b, h) do { _Pragma("unroll") for (int n = 0; n < 2; ++n) _Pragma("unroll") for (int k = 0; k < 2; ++k) dst[n][k] = *(const LAS bf16x8*)(lds + PG8_SB(b, h) + boff + n * 2048 + k * 1024); } while (0)
; #define PG8_MMA(ai, bj, At, Bt) do { __builtin_amdgcn_s_setprio(1); _Pragma("unroll") for (int m = 0; m < 4; ++m) _Pragma("unroll") for (int n = 0; n < 2; ++n) _Pragma("unroll") for (int k = 0; k < 2; ++k) \
;         acc[ai][bj][m][n] = __builtin_amdgcn_mfma_f32_16x16x32_bf16(Bt[n][k], At[m][k], acc[ai][bj][m][n], 0, 0, 0); __builtin_amdgcn_s_setprio(0); } while (0)
; #define PG8_WAIT_V(n) asm volatile("s_waitcnt vmcnt(" #n ")" ::: "memory")
; #define PG8_WAIT_L(n) asm volatile("s_waitcnt lgkmcnt(" #n ")" ::: "memory")
; #define PG8_BAR __builtin_amdgcn_s_barrier()
; #define PG8_SCHED __builtin_amdgcn_sched_barrier(0)
; template <class Epi, class Sched>
; __device__ __forceinline__ void gemm_phase(LAS unsigned char* lds, const int lda, const int ldb, const int K, const Sched& S, const Epi& E, int tid) {
;     ...
;         for (int t = 0; t < nt; t += 2) {
;             const bool last = (t == nt - 2);
;             const char* a1 = cA + (size_t)(t + 1) * kstep;
;             const char* a2 = last ? nA : cA + (size_t)(t + 2) * kstep; const char* b2 = last ? nB : cB + (size_t)(t + 2) * kstep;
;             const char* a3 = a2 + kstep; const char* b3 = b2 + kstep;
;             PG8_LDB(B0, 0, 0); PG8_LDB(B1, 0, 1); PG8_SCHED; PG8_LDA(At, 0, 0); PG8_STAGE(PG8_SA(1, 1), a1 + hA, voffA);
;             PG8_WAIT_V(8); PG8_WAIT_L(0); PG8_BAR; PG8_MMA(0, 0, At, B0); PG8_MMA(0, 1, At, B1); PG8_BAR; PG8_SCHED;
;             PG8_LDA(At, 0, 1); PG8_STAGE(PG8_SB(0, 0), b2, voffB); PG8_STAGE(PG8_SB(0, 1), b2 + hB, voffB); PG8_STAGE(PG8_SA(0, 0), a2, voffA);
;             PG8_WAIT_V(8); PG8_WAIT_L(0); PG8_BAR; PG8_MMA(1, 0, At, B0); PG8_MMA(1, 1, At, B1); PG8_BAR; PG8_SCHED;
.LBB0_91:
	s_add_u32 s10, s4, 0xfff80080
	s_addc_u32 s11, s5, -1
	s_add_i32 s22, 0, 0x10000
	s_cmp_eq_u32 s18, 28
	s_cselect_b32 s17, s3, s11
	s_cselect_b32 s16, s2, s10
	v_add_u32_e32 v0, s22, v174
	s_cselect_b32 s11, s15, s9
	s_cselect_b32 s10, s14, s7
	s_add_i32 s33, 0, 0x14000
	ds_read_b128 v[130:133], v0
	ds_read_b128 v[134:137], v0 offset:1024
	ds_read_b128 v[138:141], v0 offset:2048
	ds_read_b128 v[142:145], v0 offset:3072
	v_add_u32_e32 v0, s33, v174
	ds_read_b128 v[160:163], v0
	ds_read_b128 v[164:167], v0 offset:1024
	ds_read_b128 v[168:171], v0 offset:2048
	ds_read_b128 v[180:183], v0 offset:3072
	s_add_i32 m0, s21, 0xc000
	ds_read_b128 v[184:187], v178
	ds_read_b128 v[188:191], v178 offset:1024
	ds_read_b128 v[192:195], v178 offset:2048
	ds_read_b128 v[200:203], v178 offset:3072
	ds_read_b128 v[204:207], v178 offset:4096
	ds_read_b128 v[208:211], v178 offset:5120
	ds_read_b128 v[212:215], v178 offset:6144
	ds_read_b128 v[216:219], v178 offset:7168
	global_load_lds_dwordx4 v156, s[4:5]
	s_add_i32 m0, s21, 0xe000
	s_nop 0
	global_load_lds_dwordx4 v158, s[4:5]
	s_waitcnt vmcnt(8)
	s_waitcnt lgkmcnt(0)
	s_barrier
	s_setprio 1
	s_waitcnt lgkmcnt(0)
	v_mfma_f32_16x16x32_bf16 v[126:129], v[130:133], v[184:187], v[126:129]
	v_mfma_f32_16x16x32_bf16 v[122:125], v[138:141], v[184:187], v[122:125]
	v_mfma_f32_16x16x32_bf16 v[118:121], v[130:133], v[192:195], v[118:121]
	v_mfma_f32_16x16x32_bf16 v[110:113], v[138:141], v[192:195], v[110:113]
	v_mfma_f32_16x16x32_bf16 v[102:105], v[130:133], v[204:207], v[102:105]
	v_mfma_f32_16x16x32_bf16 v[94:97], v[138:141], v[204:207], v[94:97]
	v_mfma_f32_16x16x32_bf16 v[86:89], v[130:133], v[212:215], v[86:89]
	v_mfma_f32_16x16x32_bf16 v[78:81], v[138:141], v[212:215], v[78:81]
	v_mfma_f32_16x16x32_bf16 v[126:129], v[134:137], v[188:191], v[126:129]
	v_mfma_f32_16x16x32_bf16 v[122:125], v[142:145], v[188:191], v[122:125]
	v_mfma_f32_16x16x32_bf16 v[118:121], v[134:137], v[200:203], v[118:121]
	v_mfma_f32_16x16x32_bf16 v[110:113], v[142:145], v[200:203], v[110:113]
	v_mfma_f32_16x16x32_bf16 v[102:105], v[134:137], v[208:211], v[102:105]
	v_mfma_f32_16x16x32_bf16 v[94:97], v[142:145], v[208:211], v[94:97]
	v_mfma_f32_16x16x32_bf16 v[86:89], v[134:137], v[216:219], v[86:89]
	v_mfma_f32_16x16x32_bf16 v[78:81], v[142:145], v[216:219], v[78:81]
	s_setprio 0
	s_setprio 1
	v_mfma_f32_16x16x32_bf16 v[114:117], v[160:163], v[184:187], v[114:117]
	v_mfma_f32_16x16x32_bf16 v[106:109], v[168:171], v[184:187], v[106:109]
	v_mfma_f32_16x16x32_bf16 v[98:101], v[160:163], v[192:195], v[98:101]
	v_mfma_f32_16x16x32_bf16 v[90:93], v[168:171], v[192:195], v[90:93]
	v_mfma_f32_16x16x32_bf16 v[82:85], v[160:163], v[204:207], v[82:85]
	v_mfma_f32_16x16x32_bf16 v[74:77], v[168:171], v[204:207], v[74:77]
	v_mfma_f32_16x16x32_bf16 v[70:73], v[160:163], v[212:215], v[70:73]
	v_mfma_f32_16x16x32_bf16 v[66:69], v[168:171], v[212:215], v[66:69]
	v_mfma_f32_16x16x32_bf16 v[114:117], v[164:167], v[188:191], v[114:117]
	v_mfma_f32_16x16x32_bf16 v[106:109], v[180:183], v[188:191], v[106:109]
	v_mfma_f32_16x16x32_bf16 v[98:101], v[164:167], v[200:203], v[98:101]
	v_mfma_f32_16x16x32_bf16 v[90:93], v[180:183], v[200:203], v[90:93]
	v_mfma_f32_16x16x32_bf16 v[82:85], v[164:167], v[208:211], v[82:85]
	v_mfma_f32_16x16x32_bf16 v[74:77], v[180:183], v[208:211], v[74:77]
	v_mfma_f32_16x16x32_bf16 v[70:73], v[164:167], v[216:219], v[70:73]
	v_mfma_f32_16x16x32_bf16 v[66:69], v[180:183], v[216:219], v[66:69]
	s_setprio 0
	s_barrier
	s_add_u32 s98, s10, s30
	s_addc_u32 s99, s11, s31
	s_add_u32 s100, s16, s30
	s_addc_u32 s101, s17, s31
	s_add_i32 s22, s22, s20
	s_mov_b32 m0, s22
	ds_read_b128 v[184:187], v178 offset:16384
	ds_read_b128 v[188:191], v178 offset:17408
	ds_read_b128 v[192:195], v178 offset:18432
	ds_read_b128 v[200:203], v178 offset:19456
	ds_read_b128 v[204:207], v178 offset:20480
	ds_read_b128 v[208:211], v178 offset:21504
	ds_read_b128 v[212:215], v178 offset:22528
	ds_read_b128 v[216:219], v178 offset:23552
	global_load_lds_dwordx4 v148, s[10:11]
	s_add_i32 m0, s22, 0x2000
	s_add_u32 s22, s10, 0x80000
	s_addc_u32 s23, s11, 0
	s_add_i32 s33, s33, s20
	global_load_lds_dwordx4 v152, s[10:11]
	s_mov_b32 m0, s33
	s_nop 0
	global_load_lds_dwordx4 v148, s[22:23]
	s_add_i32 m0, s33, 0x2000
	s_nop 0
	global_load_lds_dwordx4 v152, s[22:23]
	s_mov_b32 m0, s21
	s_nop 0
	global_load_lds_dwordx4 v146, s[16:17]
	s_mov_b32 m0, s25
	s_nop 0
	global_load_lds_dwordx4 v150, s[16:17]
	s_waitcnt vmcnt(8)
	s_waitcnt lgkmcnt(0)
	s_barrier
; #define PG8_STAGE(bufoff, gbase, voff) do { _Pragma("unroll") for (int _i = 0; _i < 2; ++_i) \
;         __builtin_amdgcn_global_load_lds((const unsigned*)((const char*)(gbase) + (voff)[_i]), (LAS unsigned*)(lds + (bufoff) + ldsw + _i * 8192), 16, 0, 0); } while (0)
; #define PG8_LDA(dst, b, h) do { _Pragma("unroll") for (int m = 0; m < 4; ++m) _Pragma("unroll") for (int k = 0; k < 2; ++k) dst[m][k] = *(const LAS bf16x8*)(lds + PG8_SA(b, h) + aoff + m * 2048 + k * 1024); } while (0)
; #define PG8_LDB(dst, b, h) do { _Pragma("unroll") for (int n = 0; n < 2; ++n) _Pragma("unroll") for (int k = 0; k < 2; ++k) dst[n][k] = *(const LAS bf16x8*)(lds + PG8_SB(b, h) + boff + n * 2048 + k * 1024); } while (0)
; #define PG8_MMA(ai, bj, At, Bt) do { __builtin_amdgcn_s_setprio(1); _Pragma("unroll") for (int m = 0; m < 4; ++m) _Pragma("unroll") for (int n = 0; n < 2; ++n) _Pragma("unroll") for (int k = 0; k < 2; ++k) \
;         acc[ai][bj][m][n] = __builtin_amdgcn_mfma_f32_16x16x32_bf16(Bt[n][k], At[m][k], acc[ai][bj][m][n], 0, 0, 0); __builtin_amdgcn_s_setprio(0); } while (0)
; #define PG8_WAIT_V(n) asm volatile("s_waitcnt vmcnt(" #n ")" ::: "memory")
; #define PG8_WAIT_L(n) asm volatile("s_waitcnt lgkmcnt(" #n ")" ::: "memory")
; #define PG8_BAR __builtin_amdgcn_s_barrier()
; #define PG8_SCHED __builtin_amdgcn_sched_barrier(0)
; template <class Epi, class Sched>
; __device__ __forceinline__ void gemm_phase(LAS unsigned char* lds, const int lda, const int ldb, const int K, const Sched& S, const Epi& E, int tid) {
;     ...
;             PG8_WAIT_V(8); PG8_WAIT_L(0); PG8_BAR; PG8_MMA(1, 0, At, B0); PG8_MMA(1, 1, At, B1); PG8_BAR; PG8_SCHED;
;             PG8_LDB(B0, 1, 0); PG8_LDB(B1, 1, 1); PG8_SCHED; PG8_LDA(At, 1, 0); PG8_STAGE(PG8_SA(0, 1), a2 + hA, voffA);
;             PG8_WAIT_V(8); PG8_WAIT_L(0); PG8_BAR; PG8_MMA(0, 0, At, B0); PG8_MMA(0, 1, At, B1); PG8_BAR; PG8_SCHED;
	s_setprio 1
	s_waitcnt lgkmcnt(0)
	v_mfma_f32_16x16x32_bf16 v[62:65], v[130:133], v[184:187], v[62:65]
	v_mfma_f32_16x16x32_bf16 v[58:61], v[138:141], v[184:187], v[58:61]
	v_mfma_f32_16x16x32_bf16 v[54:57], v[130:133], v[192:195], v[54:57]
	v_mfma_f32_16x16x32_bf16 v[46:49], v[138:141], v[192:195], v[46:49]
	v_mfma_f32_16x16x32_bf16 v[38:41], v[130:133], v[204:207], v[38:41]
	v_mfma_f32_16x16x32_bf16 v[30:33], v[138:141], v[204:207], v[30:33]
	v_mfma_f32_16x16x32_bf16 v[22:25], v[130:133], v[212:215], v[22:25]
	v_mfma_f32_16x16x32_bf16 v[14:17], v[138:141], v[212:215], v[14:17]
	v_mfma_f32_16x16x32_bf16 v[62:65], v[134:137], v[188:191], v[62:65]
	v_mfma_f32_16x16x32_bf16 v[58:61], v[142:145], v[188:191], v[58:61]
	v_mfma_f32_16x16x32_bf16 v[54:57], v[134:137], v[200:203], v[54:57]
	v_mfma_f32_16x16x32_bf16 v[46:49], v[142:145], v[200:203], v[46:49]
	v_mfma_f32_16x16x32_bf16 v[38:41], v[134:137], v[208:211], v[38:41]
	v_mfma_f32_16x16x32_bf16 v[30:33], v[142:145], v[208:211], v[30:33]
	v_mfma_f32_16x16x32_bf16 v[22:25], v[134:137], v[216:219], v[22:25]
	v_mfma_f32_16x16x32_bf16 v[14:17], v[142:145], v[216:219], v[14:17]
	s_setprio 0
	s_setprio 1
	v_mfma_f32_16x16x32_bf16 v[50:53], v[160:163], v[184:187], v[50:53]
	v_mfma_f32_16x16x32_bf16 v[42:45], v[168:171], v[184:187], v[42:45]
	v_mfma_f32_16x16x32_bf16 v[34:37], v[160:163], v[192:195], v[34:37]
	v_mfma_f32_16x16x32_bf16 v[26:29], v[168:171], v[192:195], v[26:29]
	v_mfma_f32_16x16x32_bf16 v[18:21], v[160:163], v[204:207], v[18:21]
	v_mfma_f32_16x16x32_bf16 v[10:13], v[168:171], v[204:207], v[10:13]
	v_mfma_f32_16x16x32_bf16 v[6:9], v[160:163], v[212:215], v[6:9]
	v_mfma_f32_16x16x32_bf16 v[2:5], v[168:171], v[212:215], v[2:5]
	v_mfma_f32_16x16x32_bf16 v[50:53], v[164:167], v[188:191], v[50:53]
	v_mfma_f32_16x16x32_bf16 v[42:45], v[180:183], v[188:191], v[42:45]
	v_mfma_f32_16x16x32_bf16 v[34:37], v[164:167], v[200:203], v[34:37]
	v_mfma_f32_16x16x32_bf16 v[26:29], v[180:183], v[200:203], v[26:29]
	v_mfma_f32_16x16x32_bf16 v[18:21], v[164:167], v[208:211], v[18:21]
	v_mfma_f32_16x16x32_bf16 v[10:13], v[180:183], v[208:211], v[10:13]
	v_mfma_f32_16x16x32_bf16 v[6:9], v[164:167], v[216:219], v[6:9]
	v_mfma_f32_16x16x32_bf16 v[2:5], v[180:183], v[216:219], v[2:5]
	s_setprio 0
	s_barrier
	s_add_i32 s22, 0, 0x18000
	v_add_u32_e32 v0, s22, v174
	s_add_i32 s23, 0, 0x1c000
	ds_read_b128 v[130:133], v0
	ds_read_b128 v[134:137], v0 offset:1024
	ds_read_b128 v[138:141], v0 offset:2048
	ds_read_b128 v[142:145], v0 offset:3072
	v_add_u32_e32 v0, s23, v174
	ds_read_b128 v[160:163], v0
	ds_read_b128 v[164:167], v0 offset:1024
	ds_read_b128 v[168:171], v0 offset:2048
	ds_read_b128 v[180:183], v0 offset:3072
	s_add_u32 s16, s16, 0x80000
	s_addc_u32 s17, s17, 0
	s_mov_b32 m0, s26
	ds_read_b128 v[184:187], v178 offset:32768
	ds_read_b128 v[188:191], v178 offset:33792
	ds_read_b128 v[192:195], v178 offset:34816
	ds_read_b128 v[200:203], v178 offset:35840
	ds_read_b128 v[204:207], v178 offset:36864
	ds_read_b128 v[208:211], v178 offset:37888
	ds_read_b128 v[212:215], v178 offset:38912
	ds_read_b128 v[216:219], v178 offset:39936
	global_load_lds_dwordx4 v146, s[16:17]
	s_mov_b32 m0, s27
	s_nop 0
	global_load_lds_dwordx4 v150, s[16:17]
	s_waitcnt vmcnt(8)
	s_waitcnt lgkmcnt(0)
	s_barrier
	s_setprio 1
	s_waitcnt lgkmcnt(0)
	v_mfma_f32_16x16x32_bf16 v[126:129], v[130:133], v[184:187], v[126:129]
	v_mfma_f32_16x16x32_bf16 v[122:125], v[138:141], v[184:187], v[122:125]
	v_mfma_f32_16x16x32_bf16 v[118:121], v[130:133], v[192:195], v[118:121]
	v_mfma_f32_16x16x32_bf16 v[110:113], v[138:141], v[192:195], v[110:113]
	v_mfma_f32_16x16x32_bf16 v[102:105], v[130:133], v[204:207], v[102:105]
	v_mfma_f32_16x16x32_bf16 v[94:97], v[138:141], v[204:207], v[94:97]
	v_mfma_f32_16x16x32_bf16 v[86:89], v[130:133], v[212:215], v[86:89]
	v_mfma_f32_16x16x32_bf16 v[78:81], v[138:141], v[212:215], v[78:81]
	v_mfma_f32_16x16x32_bf16 v[126:129], v[134:137], v[188:191], v[126:129]
	v_mfma_f32_16x16x32_bf16 v[122:125], v[142:145], v[188:191], v[122:125]
	v_mfma_f32_16x16x32_bf16 v[118:121], v[134:137], v[200:203], v[118:121]
	v_mfma_f32_16x16x32_bf16 v[110:113], v[142:145], v[200:203], v[110:113]
	v_mfma_f32_16x16x32_bf16 v[102:105], v[134:137], v[208:211], v[102:105]
	v_mfma_f32_16x16x32_bf16 v[94:97], v[142:145], v[208:211], v[94:97]
	v_mfma_f32_16x16x32_bf16 v[86:89], v[134:137], v[216:219], v[86:89]
	v_mfma_f32_16x16x32_bf16 v[78:81], v[142:145], v[216:219], v[78:81]
	s_setprio 0
	s_setprio 1
	v_mfma_f32_16x16x32_bf16 v[114:117], v[160:163], v[184:187], v[114:117]
	v_mfma_f32_16x16x32_bf16 v[106:109], v[168:171], v[184:187], v[106:109]
	v_mfma_f32_16x16x32_bf16 v[98:101], v[160:163], v[192:195], v[98:101]
	v_mfma_f32_16x16x32_bf16 v[90:93], v[168:171], v[192:195], v[90:93]
	v_mfma_f32_16x16x32_bf16 v[82:85], v[160:163], v[204:207], v[82:85]
	v_mfma_f32_16x16x32_bf16 v[74:77], v[168:171], v[204:207], v[74:77]
	v_mfma_f32_16x16x32_bf16 v[70:73], v[160:163], v[212:215], v[70:73]
	v_mfma_f32_16x16x32_bf16 v[66:69], v[168:171], v[212:215], v[66:69]
	v_mfma_f32_16x16x32_bf16 v[114:117], v[164:167], v[188:191], v[114:117]
	v_mfma_f32_16x16x32_bf16 v[106:109], v[180:183], v[188:191], v[106:109]
	v_mfma_f32_16x16x32_bf16 v[98:101], v[164:167], v[200:203], v[98:101]
	v_mfma_f32_16x16x32_bf16 v[90:93], v[180:183], v[200:203], v[90:93]
	v_mfma_f32_16x16x32_bf16 v[82:85], v[164:167], v[208:211], v[82:85]
	v_mfma_f32_16x16x32_bf16 v[74:77], v[180:183], v[208:211], v[74:77]
	v_mfma_f32_16x16x32_bf16 v[70:73], v[164:167], v[216:219], v[70:73]
	v_mfma_f32_16x16x32_bf16 v[66:69], v[180:183], v[216:219], v[66:69]
	s_setprio 0
	s_barrier
; #define PG8_STAGE(bufoff, gbase, voff) do { _Pragma("unroll") for (int _i = 0; _i < 2; ++_i) \
;         __builtin_amdgcn_global_load_lds((const unsigned*)((const char*)(gbase) + (voff)[_i]), (LAS unsigned*)(lds + (bufoff) + ldsw + _i * 8192), 16, 0, 0); } while (0)
; #define PG8_LDA(dst, b, h) do { _Pragma("unroll") for (int m = 0; m < 4; ++m) _Pragma("unroll") for (int k = 0; k < 2; ++k) dst[m][k] = *(const LAS bf16x8*)(lds + PG8_SA(b, h) + aoff + m * 2048 + k * 1024); } while (0)
; #define PG8_MMA(ai, bj, At, Bt) do { __builtin_amdgcn_s_setprio(1); _Pragma("unroll") for (int m = 0; m < 4; ++m) _Pragma("unroll") for (int n = 0; n < 2; ++n) _Pragma("unroll") for (int k = 0; k < 2; ++k) \
;         acc[ai][bj][m][n] = __builtin_amdgcn_mfma_f32_16x16x32_bf16(Bt[n][k], At[m][k], acc[ai][bj][m][n], 0, 0, 0); __builtin_amdgcn_s_setprio(0); } while (0)
; #define PG8_WAIT_V(n) asm volatile("s_waitcnt vmcnt(" #n ")" ::: "memory")
; #define PG8_WAIT_L(n) asm volatile("s_waitcnt lgkmcnt(" #n ")" ::: "memory")
; #define PG8_BAR __builtin_amdgcn_s_barrier()
; #define PG8_SCHED __builtin_amdgcn_sched_barrier(0)
; template <class Epi, class Sched>
; __device__ __forceinline__ void gemm_phase(LAS unsigned char* lds, const int lda, const int ldb, const int K, const Sched& S, const Epi& E, int tid) {
;     ...
;             PG8_LDA(At, 1, 1); PG8_STAGE(PG8_SB(1, 0), b3, voffB); PG8_STAGE(PG8_SB(1, 1), b3 + hB, voffB); PG8_STAGE(PG8_SA(1, 0), a3, voffA);
;             PG8_WAIT_V(8); PG8_WAIT_L(0); PG8_BAR; PG8_MMA(1, 0, At, B0); PG8_MMA(1, 1, At, B1); PG8_BAR; PG8_SCHED;
;         }
	s_add_i32 s16, s22, s20
	s_mov_b32 m0, s16
	ds_read_b128 v[184:187], v178 offset:49152
	ds_read_b128 v[188:191], v178 offset:50176
	ds_read_b128 v[192:195], v178 offset:51200
	ds_read_b128 v[200:203], v178 offset:52224
	ds_read_b128 v[204:207], v178 offset:53248
	ds_read_b128 v[208:211], v178 offset:54272
	ds_read_b128 v[212:215], v178 offset:55296
	ds_read_b128 v[216:219], v178 offset:56320
	global_load_lds_dwordx4 v148, s[98:99]
	s_add_i32 m0, s16, 0x2000
	s_add_u32 s10, s10, 0x80080
	s_addc_u32 s11, s11, 0
	s_add_i32 s16, s23, s20
	global_load_lds_dwordx4 v152, s[98:99]
	s_mov_b32 m0, s16
	s_nop 0
	global_load_lds_dwordx4 v148, s[10:11]
	s_add_i32 m0, s16, 0x2000
	s_nop 0
	global_load_lds_dwordx4 v152, s[10:11]
	s_mov_b32 m0, s54
	s_nop 0
	global_load_lds_dwordx4 v146, s[100:101]
	s_mov_b32 m0, s55
	s_nop 0
	global_load_lds_dwordx4 v150, s[100:101]
	s_waitcnt vmcnt(8)
	s_waitcnt lgkmcnt(0)
	s_barrier
	s_setprio 1
	s_waitcnt lgkmcnt(0)
	v_mfma_f32_16x16x32_bf16 v[62:65], v[130:133], v[184:187], v[62:65]
	v_mfma_f32_16x16x32_bf16 v[58:61], v[138:141], v[184:187], v[58:61]
	v_mfma_f32_16x16x32_bf16 v[54:57], v[130:133], v[192:195], v[54:57]
	v_mfma_f32_16x16x32_bf16 v[46:49], v[138:141], v[192:195], v[46:49]
	v_mfma_f32_16x16x32_bf16 v[38:41], v[130:133], v[204:207], v[38:41]
	v_mfma_f32_16x16x32_bf16 v[30:33], v[138:141], v[204:207], v[30:33]
	v_mfma_f32_16x16x32_bf16 v[22:25], v[130:133], v[212:215], v[22:25]
	v_mfma_f32_16x16x32_bf16 v[14:17], v[138:141], v[212:215], v[14:17]
	v_mfma_f32_16x16x32_bf16 v[62:65], v[134:137], v[188:191], v[62:65]
	v_mfma_f32_16x16x32_bf16 v[58:61], v[142:145], v[188:191], v[58:61]
	v_mfma_f32_16x16x32_bf16 v[54:57], v[134:137], v[200:203], v[54:57]
	v_mfma_f32_16x16x32_bf16 v[46:49], v[142:145], v[200:203], v[46:49]
	v_mfma_f32_16x16x32_bf16 v[38:41], v[134:137], v[208:211], v[38:41]
	v_mfma_f32_16x16x32_bf16 v[30:33], v[142:145], v[208:211], v[30:33]
	v_mfma_f32_16x16x32_bf16 v[22:25], v[134:137], v[216:219], v[22:25]
	v_mfma_f32_16x16x32_bf16 v[14:17], v[142:145], v[216:219], v[14:17]
	s_setprio 0
	s_setprio 1
	v_mfma_f32_16x16x32_bf16 v[50:53], v[160:163], v[184:187], v[50:53]
	v_mfma_f32_16x16x32_bf16 v[42:45], v[168:171], v[184:187], v[42:45]
	v_mfma_f32_16x16x32_bf16 v[34:37], v[160:163], v[192:195], v[34:37]
	v_mfma_f32_16x16x32_bf16 v[26:29], v[168:171], v[192:195], v[26:29]
	v_mfma_f32_16x16x32_bf16 v[18:21], v[160:163], v[204:207], v[18:21]
	v_mfma_f32_16x16x32_bf16 v[10:13], v[168:171], v[204:207], v[10:13]
	v_mfma_f32_16x16x32_bf16 v[6:9], v[160:163], v[212:215], v[6:9]
	v_mfma_f32_16x16x32_bf16 v[2:5], v[168:171], v[212:215], v[2:5]
	v_mfma_f32_16x16x32_bf16 v[50:53], v[164:167], v[188:191], v[50:53]
	v_mfma_f32_16x16x32_bf16 v[42:45], v[180:183], v[188:191], v[42:45]
	v_mfma_f32_16x16x32_bf16 v[34:37], v[164:167], v[200:203], v[34:37]
	v_mfma_f32_16x16x32_bf16 v[26:29], v[180:183], v[200:203], v[26:29]
	v_mfma_f32_16x16x32_bf16 v[18:21], v[164:167], v[208:211], v[18:21]
	v_mfma_f32_16x16x32_bf16 v[10:13], v[180:183], v[208:211], v[10:13]
	v_mfma_f32_16x16x32_bf16 v[6:9], v[164:167], v[216:219], v[6:9]
	v_mfma_f32_16x16x32_bf16 v[2:5], v[180:183], v[216:219], v[2:5]
	s_setprio 0
	s_barrier
	s_add_i32 s18, s18, 2
	s_add_u32 s4, s4, 0x100
	s_addc_u32 s5, s5, 0
	s_add_u32 s7, s7, 0x100
	s_addc_u32 s9, s9, 0
	s_cmp_gt_u32 s18, 29
	s_cbranch_scc0 .LBB0_91
	s_and_b64 vcc, exec, s[46:47]
	s_cbranch_vccz .LBB0_94
	s_barrier

; #define PG8_STAGE(bufoff, gbase, voff) do { _Pragma("unroll") for (int _i = 0; _i < 2; ++_i) \
;         __builtin_amdgcn_global_load_lds((const unsigned*)((const char*)(gbase) + (voff)[_i]), (LAS unsigned*)(lds + (bufoff) + ldsw + _i * 8192), 16, 0, 0); } while (0)
; #define PG8_LDA(dst, b, h) do { _Pragma("unroll") for (int m = 0; m < 4; ++m) _Pragma("unroll") for (int k = 0; k < 2; ++k) dst[m][k] = *(const LAS bf16x8*)(lds + PG8_SA(b, h) + aoff + m * 2048 + k * 1024); } while (0)
; #define PG8_LDB(dst, b, h) do { _Pragma("unroll") for (int n = 0; n < 2; ++n) _Pragma("unroll") for (int k = 0; k < 2; ++k) dst[n][k] = *(const LAS bf16x8*)(lds + PG8_SB(b, h) + boff + n * 2048 + k * 1024); } while (0)
; #define PG8_MMA(ai, bj, At, Bt) do { __builtin_amdgcn_s_setprio(1); _Pragma("unroll") for (int m = 0; m < 4; ++m) _Pragma("unroll") for (int n = 0; n < 2; ++n) _Pragma("unroll") for (int k = 0; k < 2; ++k) \
;         acc[ai][bj][m][n] = __builtin_amdgcn_mfma_f32_16x16x32_bf16(Bt[n][k], At[m][k], acc[ai][bj][m][n], 0, 0, 0); __builtin_amdgcn_s_setprio(0); } while (0)
; #define PG8_WAIT_V(n) asm volatile("s_waitcnt vmcnt(" #n ")" ::: "memory")
; #define PG8_WAIT_L(n) asm volatile("s_waitcnt lgkmcnt(" #n ")" ::: "memory")
; #define PG8_BAR __builtin_amdgcn_s_barrier()
; #define PG8_SCHED __builtin_amdgcn_sched_barrier(0)
; template <class Epi, class Sched>
; __device__ __forceinline__ void gemm_phase(LAS unsigned char* lds, const int lda, const int ldb, const int K, const Sched& S, const Epi& E, int tid) {
;     ...
;         for (int t = 0; t < nt; t += 2) {
;             const bool last = (t == nt - 2);
;             const char* a1 = cA + (size_t)(t + 1) * kstep;
;             const char* a2 = last ? nA : cA + (size_t)(t + 2) * kstep; const char* b2 = last ? nB : cB + (size_t)(t + 2) * kstep;
;             const char* a3 = a2 + kstep; const char* b3 = b2 + kstep;
;             PG8_LDB(B0, 0, 0); PG8_LDB(B1, 0, 1); PG8_SCHED; PG8_LDA(At, 0, 0); PG8_STAGE(PG8_SA(1, 1), a1 + hA, voffA);
;             PG8_WAIT_V(8); PG8_WAIT_L(0); PG8_BAR; PG8_MMA(0, 0, At, B0); PG8_MMA(0, 1, At, B1); PG8_BAR; PG8_SCHED;
;             PG8_LDA(At, 0, 1); PG8_STAGE(PG8_SB(0, 0), b2, voffB); PG8_STAGE(PG8_SB(0, 1), b2 + hB, voffB); PG8_STAGE(PG8_SA(0, 0), a2, voffA);
;             PG8_WAIT_V(8); PG8_WAIT_L(0); PG8_BAR; PG8_MMA(1, 0, At, B0); PG8_MMA(1, 1, At, B1); PG8_BAR; PG8_SCHED;
.LBB0_262:
	s_add_u32 s10, s8, 0xfff80080
	s_addc_u32 s11, s9, -1
	s_add_i32 s34, 0, 0x10000
	s_cmp_eq_u32 s43, 28
	s_cselect_b32 s15, s5, s11
	s_cselect_b32 s14, s4, s10
	s_cselect_b32 s11, s7, s42
	s_cselect_b32 s10, s6, s33
	s_add_i32 s35, 0, 0x14000
	v_add_u32_e32 v160, s34, v145
	v_add_u32_e32 v176, s35, v145
	ds_read_b128 v[148:151], v160
	ds_read_b128 v[152:155], v160 offset:1024
	ds_read_b128 v[156:159], v160 offset:2048
	ds_read_b128 v[160:163], v160 offset:3072
	ds_read_b128 v[164:167], v176
	ds_read_b128 v[168:171], v176 offset:1024
	ds_read_b128 v[172:175], v176 offset:2048
	ds_read_b128 v[176:179], v176 offset:3072
	s_add_i32 m0, s17, 0xc000
	ds_read_b128 v[180:183], v147
	ds_read_b128 v[184:187], v147 offset:1024
	ds_read_b128 v[188:191], v147 offset:2048
	ds_read_b128 v[192:195], v147 offset:3072
	ds_read_b128 v[200:203], v147 offset:4096
	ds_read_b128 v[204:207], v147 offset:5120
	ds_read_b128 v[208:211], v147 offset:6144
	ds_read_b128 v[212:215], v147 offset:7168
	global_load_lds_dwordx4 v140, s[8:9]
	s_add_i32 m0, s17, 0xe000
	s_nop 0
	global_load_lds_dwordx4 v142, s[8:9]
	s_waitcnt vmcnt(8)
	s_waitcnt lgkmcnt(0)
	s_barrier
	s_setprio 1
	s_waitcnt lgkmcnt(0)
	v_mfma_f32_16x16x32_bf16 v[126:129], v[148:151], v[180:183], v[126:129]
	v_mfma_f32_16x16x32_bf16 v[122:125], v[156:159], v[180:183], v[122:125]
	v_mfma_f32_16x16x32_bf16 v[118:121], v[148:151], v[188:191], v[118:121]
	v_mfma_f32_16x16x32_bf16 v[114:117], v[156:159], v[188:191], v[114:117]
	v_mfma_f32_16x16x32_bf16 v[110:113], v[148:151], v[200:203], v[110:113]
	v_mfma_f32_16x16x32_bf16 v[102:105], v[156:159], v[200:203], v[102:105]
	v_mfma_f32_16x16x32_bf16 v[94:97], v[148:151], v[208:211], v[94:97]
	v_mfma_f32_16x16x32_bf16 v[86:89], v[156:159], v[208:211], v[86:89]
	v_mfma_f32_16x16x32_bf16 v[126:129], v[152:155], v[184:187], v[126:129]
	v_mfma_f32_16x16x32_bf16 v[122:125], v[160:163], v[184:187], v[122:125]
	v_mfma_f32_16x16x32_bf16 v[118:121], v[152:155], v[192:195], v[118:121]
	v_mfma_f32_16x16x32_bf16 v[114:117], v[160:163], v[192:195], v[114:117]
	v_mfma_f32_16x16x32_bf16 v[110:113], v[152:155], v[204:207], v[110:113]
	v_mfma_f32_16x16x32_bf16 v[102:105], v[160:163], v[204:207], v[102:105]
	v_mfma_f32_16x16x32_bf16 v[94:97], v[152:155], v[212:215], v[94:97]
	v_mfma_f32_16x16x32_bf16 v[86:89], v[160:163], v[212:215], v[86:89]
	s_setprio 0
	s_setprio 1
	v_mfma_f32_16x16x32_bf16 v[106:109], v[164:167], v[180:183], v[106:109]
	v_mfma_f32_16x16x32_bf16 v[98:101], v[172:175], v[180:183], v[98:101]
	v_mfma_f32_16x16x32_bf16 v[90:93], v[164:167], v[188:191], v[90:93]
	v_mfma_f32_16x16x32_bf16 v[82:85], v[172:175], v[188:191], v[82:85]
	v_mfma_f32_16x16x32_bf16 v[78:81], v[164:167], v[200:203], v[78:81]
	v_mfma_f32_16x16x32_bf16 v[74:77], v[172:175], v[200:203], v[74:77]
	v_mfma_f32_16x16x32_bf16 v[70:73], v[164:167], v[208:211], v[70:73]
	v_mfma_f32_16x16x32_bf16 v[66:69], v[172:175], v[208:211], v[66:69]
	v_mfma_f32_16x16x32_bf16 v[106:109], v[168:171], v[184:187], v[106:109]
	v_mfma_f32_16x16x32_bf16 v[98:101], v[176:179], v[184:187], v[98:101]
	v_mfma_f32_16x16x32_bf16 v[90:93], v[168:171], v[192:195], v[90:93]
	v_mfma_f32_16x16x32_bf16 v[82:85], v[176:179], v[192:195], v[82:85]
	v_mfma_f32_16x16x32_bf16 v[78:81], v[168:171], v[204:207], v[78:81]
	v_mfma_f32_16x16x32_bf16 v[74:77], v[176:179], v[204:207], v[74:77]
	v_mfma_f32_16x16x32_bf16 v[70:73], v[168:171], v[212:215], v[70:73]
	v_mfma_f32_16x16x32_bf16 v[66:69], v[176:179], v[212:215], v[66:69]
	s_setprio 0
	s_barrier
	s_add_u32 s98, s10, s30
	s_addc_u32 s99, s11, s31
	s_add_u32 s100, s14, s30
	s_addc_u32 s101, s15, s31
	s_add_i32 s34, s34, s16
	s_mov_b32 m0, s34
	ds_read_b128 v[180:183], v147 offset:16384
	ds_read_b128 v[184:187], v147 offset:17408
	ds_read_b128 v[188:191], v147 offset:18432
	ds_read_b128 v[192:195], v147 offset:19456
	ds_read_b128 v[200:203], v147 offset:20480
	ds_read_b128 v[204:207], v147 offset:21504
	ds_read_b128 v[208:211], v147 offset:22528
	ds_read_b128 v[212:215], v147 offset:23552
	global_load_lds_dwordx4 v132, s[10:11]
	s_add_i32 m0, s34, 0x2000
	s_add_u32 s44, s10, 0x80000
	s_addc_u32 s45, s11, 0
	s_add_i32 s34, s35, s16
	global_load_lds_dwordx4 v136, s[10:11]
	s_mov_b32 m0, s34
	s_nop 0
	global_load_lds_dwordx4 v132, s[44:45]
	s_add_i32 m0, s34, 0x2000
	s_nop 0
	global_load_lds_dwordx4 v136, s[44:45]
	s_mov_b32 m0, s17
	s_nop 0
	global_load_lds_dwordx4 v130, s[14:15]
	s_mov_b32 m0, s18
	s_nop 0
	global_load_lds_dwordx4 v134, s[14:15]
	s_waitcnt vmcnt(8)
	s_waitcnt lgkmcnt(0)
	s_barrier
; #define PG8_STAGE(bufoff, gbase, voff) do { _Pragma("unroll") for (int _i = 0; _i < 2; ++_i) \
;         __builtin_amdgcn_global_load_lds((const unsigned*)((const char*)(gbase) + (voff)[_i]), (LAS unsigned*)(lds + (bufoff) + ldsw + _i * 8192), 16, 0, 0); } while (0)
; #define PG8_LDA(dst, b, h) do { _Pragma("unroll") for (int m = 0; m < 4; ++m) _Pragma("unroll") for (int k = 0; k < 2; ++k) dst[m][k] = *(const LAS bf16x8*)(lds + PG8_SA(b, h) + aoff + m * 2048 + k * 1024); } while (0)
; #define PG8_LDB(dst, b, h) do { _Pragma("unroll") for (int n = 0; n < 2; ++n) _Pragma("unroll") for (int k = 0; k < 2; ++k) dst[n][k] = *(const LAS bf16x8*)(lds + PG8_SB(b, h) + boff + n * 2048 + k * 1024); } while (0)
; #define PG8_MMA(ai, bj, At, Bt) do { __builtin_amdgcn_s_setprio(1); _Pragma("unroll") for (int m = 0; m < 4; ++m) _Pragma("unroll") for (int n = 0; n < 2; ++n) _Pragma("unroll") for (int k = 0; k < 2; ++k) \
;         acc[ai][bj][m][n] = __builtin_amdgcn_mfma_f32_16x16x32_bf16(Bt[n][k], At[m][k], acc[ai][bj][m][n], 0, 0, 0); __builtin_amdgcn_s_setprio(0); } while (0)
; #define PG8_WAIT_V(n) asm volatile("s_waitcnt vmcnt(" #n ")" ::: "memory")
; #define PG8_WAIT_L(n) asm volatile("s_waitcnt lgkmcnt(" #n ")" ::: "memory")
; #define PG8_BAR __builtin_amdgcn_s_barrier()
; #define PG8_SCHED __builtin_amdgcn_sched_barrier(0)
; template <class Epi, class Sched>
; __device__ __forceinline__ void gemm_phase(LAS unsigned char* lds, const int lda, const int ldb, const int K, const Sched& S, const Epi& E, int tid) {
;     ...
;             PG8_WAIT_V(8); PG8_WAIT_L(0); PG8_BAR; PG8_MMA(1, 0, At, B0); PG8_MMA(1, 1, At, B1); PG8_BAR; PG8_SCHED;
;             PG8_LDB(B0, 1, 0); PG8_LDB(B1, 1, 1); PG8_SCHED; PG8_LDA(At, 1, 0); PG8_STAGE(PG8_SA(0, 1), a2 + hA, voffA);
;             PG8_WAIT_V(8); PG8_WAIT_L(0); PG8_BAR; PG8_MMA(0, 0, At, B0); PG8_MMA(0, 1, At, B1); PG8_BAR; PG8_SCHED;
	s_setprio 1
	s_waitcnt lgkmcnt(0)
	v_mfma_f32_16x16x32_bf16 v[62:65], v[148:151], v[180:183], v[62:65]
	v_mfma_f32_16x16x32_bf16 v[58:61], v[156:159], v[180:183], v[58:61]
	v_mfma_f32_16x16x32_bf16 v[54:57], v[148:151], v[188:191], v[54:57]
	v_mfma_f32_16x16x32_bf16 v[50:53], v[156:159], v[188:191], v[50:53]
	v_mfma_f32_16x16x32_bf16 v[46:49], v[148:151], v[200:203], v[46:49]
	v_mfma_f32_16x16x32_bf16 v[38:41], v[156:159], v[200:203], v[38:41]
	v_mfma_f32_16x16x32_bf16 v[30:33], v[148:151], v[208:211], v[30:33]
	v_mfma_f32_16x16x32_bf16 v[22:25], v[156:159], v[208:211], v[22:25]
	v_mfma_f32_16x16x32_bf16 v[62:65], v[152:155], v[184:187], v[62:65]
	v_mfma_f32_16x16x32_bf16 v[58:61], v[160:163], v[184:187], v[58:61]
	v_mfma_f32_16x16x32_bf16 v[54:57], v[152:155], v[192:195], v[54:57]
	v_mfma_f32_16x16x32_bf16 v[50:53], v[160:163], v[192:195], v[50:53]
	v_mfma_f32_16x16x32_bf16 v[46:49], v[152:155], v[204:207], v[46:49]
	v_mfma_f32_16x16x32_bf16 v[38:41], v[160:163], v[204:207], v[38:41]
	v_mfma_f32_16x16x32_bf16 v[30:33], v[152:155], v[212:215], v[30:33]
	v_mfma_f32_16x16x32_bf16 v[22:25], v[160:163], v[212:215], v[22:25]
	s_setprio 0
	s_setprio 1
	v_mfma_f32_16x16x32_bf16 v[42:45], v[164:167], v[180:183], v[42:45]
	v_mfma_f32_16x16x32_bf16 v[34:37], v[172:175], v[180:183], v[34:37]
	v_mfma_f32_16x16x32_bf16 v[26:29], v[164:167], v[188:191], v[26:29]
	v_mfma_f32_16x16x32_bf16 v[18:21], v[172:175], v[188:191], v[18:21]
	v_mfma_f32_16x16x32_bf16 v[14:17], v[164:167], v[200:203], v[14:17]
	v_mfma_f32_16x16x32_bf16 v[10:13], v[172:175], v[200:203], v[10:13]
	v_mfma_f32_16x16x32_bf16 v[6:9], v[164:167], v[208:211], v[6:9]
	v_mfma_f32_16x16x32_bf16 v[2:5], v[172:175], v[208:211], v[2:5]
	v_mfma_f32_16x16x32_bf16 v[42:45], v[168:171], v[184:187], v[42:45]
	v_mfma_f32_16x16x32_bf16 v[34:37], v[176:179], v[184:187], v[34:37]
	v_mfma_f32_16x16x32_bf16 v[26:29], v[168:171], v[192:195], v[26:29]
	v_mfma_f32_16x16x32_bf16 v[18:21], v[176:179], v[192:195], v[18:21]
	v_mfma_f32_16x16x32_bf16 v[14:17], v[168:171], v[204:207], v[14:17]
	v_mfma_f32_16x16x32_bf16 v[10:13], v[176:179], v[204:207], v[10:13]
	v_mfma_f32_16x16x32_bf16 v[6:9], v[168:171], v[212:215], v[6:9]
	v_mfma_f32_16x16x32_bf16 v[2:5], v[176:179], v[212:215], v[2:5]
	s_setprio 0
	s_barrier
	s_add_i32 s34, 0, 0x18000
	s_add_i32 s35, 0, 0x1c000
	v_add_u32_e32 v160, s34, v145
	v_add_u32_e32 v176, s35, v145
	ds_read_b128 v[148:151], v160
	ds_read_b128 v[152:155], v160 offset:1024
	ds_read_b128 v[156:159], v160 offset:2048
	ds_read_b128 v[160:163], v160 offset:3072
	ds_read_b128 v[164:167], v176
	ds_read_b128 v[168:171], v176 offset:1024
	ds_read_b128 v[172:175], v176 offset:2048
	ds_read_b128 v[176:179], v176 offset:3072
	s_add_u32 s14, s14, 0x80000
	s_addc_u32 s15, s15, 0
	s_mov_b32 m0, s19
	ds_read_b128 v[180:183], v147 offset:32768
	ds_read_b128 v[184:187], v147 offset:33792
	ds_read_b128 v[188:191], v147 offset:34816
	ds_read_b128 v[192:195], v147 offset:35840
	ds_read_b128 v[200:203], v147 offset:36864
	ds_read_b128 v[204:207], v147 offset:37888
	ds_read_b128 v[208:211], v147 offset:38912
	ds_read_b128 v[212:215], v147 offset:39936
	global_load_lds_dwordx4 v130, s[14:15]
	s_mov_b32 m0, s20
	s_nop 0
	global_load_lds_dwordx4 v134, s[14:15]
	s_waitcnt vmcnt(8)
	s_waitcnt lgkmcnt(0)
	s_barrier
	s_setprio 1
	s_waitcnt lgkmcnt(0)
	v_mfma_f32_16x16x32_bf16 v[126:129], v[148:151], v[180:183], v[126:129]
	v_mfma_f32_16x16x32_bf16 v[122:125], v[156:159], v[180:183], v[122:125]
	v_mfma_f32_16x16x32_bf16 v[118:121], v[148:151], v[188:191], v[118:121]
	v_mfma_f32_16x16x32_bf16 v[114:117], v[156:159], v[188:191], v[114:117]
	v_mfma_f32_16x16x32_bf16 v[110:113], v[148:151], v[200:203], v[110:113]
	v_mfma_f32_16x16x32_bf16 v[102:105], v[156:159], v[200:203], v[102:105]
	v_mfma_f32_16x16x32_bf16 v[94:97], v[148:151], v[208:211], v[94:97]
	v_mfma_f32_16x16x32_bf16 v[86:89], v[156:159], v[208:211], v[86:89]
	v_mfma_f32_16x16x32_bf16 v[126:129], v[152:155], v[184:187], v[126:129]
	v_mfma_f32_16x16x32_bf16 v[122:125], v[160:163], v[184:187], v[122:125]
	v_mfma_f32_16x16x32_bf16 v[118:121], v[152:155], v[192:195], v[118:121]
	v_mfma_f32_16x16x32_bf16 v[114:117], v[160:163], v[192:195], v[114:117]
	v_mfma_f32_16x16x32_bf16 v[110:113], v[152:155], v[204:207], v[110:113]
	v_mfma_f32_16x16x32_bf16 v[102:105], v[160:163], v[204:207], v[102:105]
	v_mfma_f32_16x16x32_bf16 v[94:97], v[152:155], v[212:215], v[94:97]
	v_mfma_f32_16x16x32_bf16 v[86:89], v[160:163], v[212:215], v[86:89]
	s_setprio 0
	s_setprio 1
	v_mfma_f32_16x16x32_bf16 v[106:109], v[164:167], v[180:183], v[106:109]
	v_mfma_f32_16x16x32_bf16 v[98:101], v[172:175], v[180:183], v[98:101]
	v_mfma_f32_16x16x32_bf16 v[90:93], v[164:167], v[188:191], v[90:93]
	v_mfma_f32_16x16x32_bf16 v[82:85], v[172:175], v[188:191], v[82:85]
	v_mfma_f32_16x16x32_bf16 v[78:81], v[164:167], v[200:203], v[78:81]
	v_mfma_f32_16x16x32_bf16 v[74:77], v[172:175], v[200:203], v[74:77]
	v_mfma_f32_16x16x32_bf16 v[70:73], v[164:167], v[208:211], v[70:73]
	v_mfma_f32_16x16x32_bf16 v[66:69], v[172:175], v[208:211], v[66:69]
	v_mfma_f32_16x16x32_bf16 v[106:109], v[168:171], v[184:187], v[106:109]
	v_mfma_f32_16x16x32_bf16 v[98:101], v[176:179], v[184:187], v[98:101]
	v_mfma_f32_16x16x32_bf16 v[90:93], v[168:171], v[192:195], v[90:93]
	v_mfma_f32_16x16x32_bf16 v[82:85], v[176:179], v[192:195], v[82:85]
	v_mfma_f32_16x16x32_bf16 v[78:81], v[168:171], v[204:207], v[78:81]
	v_mfma_f32_16x16x32_bf16 v[74:77], v[176:179], v[204:207], v[74:77]
	v_mfma_f32_16x16x32_bf16 v[70:73], v[168:171], v[212:215], v[70:73]
	v_mfma_f32_16x16x32_bf16 v[66:69], v[176:179], v[212:215], v[66:69]
	s_setprio 0
	s_barrier
; #define PG8_STAGE(bufoff, gbase, voff) do { _Pragma("unroll") for (int _i = 0; _i < 2; ++_i) \
;         __builtin_amdgcn_global_load_lds((const unsigned*)((const char*)(gbase) + (voff)[_i]), (LAS unsigned*)(lds + (bufoff) + ldsw + _i * 8192), 16, 0, 0); } while (0)
; #define PG8_LDA(dst, b, h) do { _Pragma("unroll") for (int m = 0; m < 4; ++m) _Pragma("unroll") for (int k = 0; k < 2; ++k) dst[m][k] = *(const LAS bf16x8*)(lds + PG8_SA(b, h) + aoff + m * 2048 + k * 1024); } while (0)
; #define PG8_MMA(ai, bj, At, Bt) do { __builtin_amdgcn_s_setprio(1); _Pragma("unroll") for (int m = 0; m < 4; ++m) _Pragma("unroll") for (int n = 0; n < 2; ++n) _Pragma("unroll") for (int k = 0; k < 2; ++k) \
;         acc[ai][bj][m][n] = __builtin_amdgcn_mfma_f32_16x16x32_bf16(Bt[n][k], At[m][k], acc[ai][bj][m][n], 0, 0, 0); __builtin_amdgcn_s_setprio(0); } while (0)
; #define PG8_WAIT_V(n) asm volatile("s_waitcnt vmcnt(" #n ")" ::: "memory")
; #define PG8_WAIT_L(n) asm volatile("s_waitcnt lgkmcnt(" #n ")" ::: "memory")
; #define PG8_BAR __builtin_amdgcn_s_barrier()
; #define PG8_SCHED __builtin_amdgcn_sched_barrier(0)
; template <class Epi, class Sched>
; __device__ __forceinline__ void gemm_phase(LAS unsigned char* lds, const int lda, const int ldb, const int K, const Sched& S, const Epi& E, int tid) {
;     ...
;             PG8_LDA(At, 1, 1); PG8_STAGE(PG8_SB(1, 0), b3, voffB); PG8_STAGE(PG8_SB(1, 1), b3 + hB, voffB); PG8_STAGE(PG8_SA(1, 0), a3, voffA);
;             PG8_WAIT_V(8); PG8_WAIT_L(0); PG8_BAR; PG8_MMA(1, 0, At, B0); PG8_MMA(1, 1, At, B1); PG8_BAR; PG8_SCHED;
;         }
	s_add_i32 s14, s34, s16
	s_mov_b32 m0, s14
	ds_read_b128 v[180:183], v147 offset:49152
	ds_read_b128 v[184:187], v147 offset:50176
	ds_read_b128 v[188:191], v147 offset:51200
	ds_read_b128 v[192:195], v147 offset:52224
	ds_read_b128 v[200:203], v147 offset:53248
	ds_read_b128 v[204:207], v147 offset:54272
	ds_read_b128 v[208:211], v147 offset:55296
	ds_read_b128 v[212:215], v147 offset:56320
	global_load_lds_dwordx4 v132, s[98:99]
	s_add_i32 m0, s14, 0x2000
	s_add_u32 s10, s10, 0x80080
	s_addc_u32 s11, s11, 0
	s_add_i32 s14, s35, s16
	global_load_lds_dwordx4 v136, s[98:99]
	s_mov_b32 m0, s14
	s_nop 0
	global_load_lds_dwordx4 v132, s[10:11]
	s_add_i32 m0, s14, 0x2000
	s_nop 0
	global_load_lds_dwordx4 v136, s[10:11]
	s_mov_b32 m0, s21
	s_nop 0
	global_load_lds_dwordx4 v130, s[100:101]
	s_mov_b32 m0, s22
	s_nop 0
	global_load_lds_dwordx4 v134, s[100:101]
	s_waitcnt vmcnt(8)
	s_waitcnt lgkmcnt(0)
	s_barrier
	s_setprio 1
	s_waitcnt lgkmcnt(0)
	v_mfma_f32_16x16x32_bf16 v[62:65], v[148:151], v[180:183], v[62:65]
	v_mfma_f32_16x16x32_bf16 v[58:61], v[156:159], v[180:183], v[58:61]
	v_mfma_f32_16x16x32_bf16 v[54:57], v[148:151], v[188:191], v[54:57]
	v_mfma_f32_16x16x32_bf16 v[50:53], v[156:159], v[188:191], v[50:53]
	v_mfma_f32_16x16x32_bf16 v[46:49], v[148:151], v[200:203], v[46:49]
	v_mfma_f32_16x16x32_bf16 v[38:41], v[156:159], v[200:203], v[38:41]
	v_mfma_f32_16x16x32_bf16 v[30:33], v[148:151], v[208:211], v[30:33]
	v_mfma_f32_16x16x32_bf16 v[22:25], v[156:159], v[208:211], v[22:25]
	v_mfma_f32_16x16x32_bf16 v[62:65], v[152:155], v[184:187], v[62:65]
	v_mfma_f32_16x16x32_bf16 v[58:61], v[160:163], v[184:187], v[58:61]
	v_mfma_f32_16x16x32_bf16 v[54:57], v[152:155], v[192:195], v[54:57]
	v_mfma_f32_16x16x32_bf16 v[50:53], v[160:163], v[192:195], v[50:53]
	v_mfma_f32_16x16x32_bf16 v[46:49], v[152:155], v[204:207], v[46:49]
	v_mfma_f32_16x16x32_bf16 v[38:41], v[160:163], v[204:207], v[38:41]
	v_mfma_f32_16x16x32_bf16 v[30:33], v[152:155], v[212:215], v[30:33]
	v_mfma_f32_16x16x32_bf16 v[22:25], v[160:163], v[212:215], v[22:25]
	s_setprio 0
	s_setprio 1
	v_mfma_f32_16x16x32_bf16 v[42:45], v[164:167], v[180:183], v[42:45]
	v_mfma_f32_16x16x32_bf16 v[34:37], v[172:175], v[180:183], v[34:37]
	v_mfma_f32_16x16x32_bf16 v[26:29], v[164:167], v[188:191], v[26:29]
	v_mfma_f32_16x16x32_bf16 v[18:21], v[172:175], v[188:191], v[18:21]
	v_mfma_f32_16x16x32_bf16 v[14:17], v[164:167], v[200:203], v[14:17]
	v_mfma_f32_16x16x32_bf16 v[10:13], v[172:175], v[200:203], v[10:13]
	v_mfma_f32_16x16x32_bf16 v[6:9], v[164:167], v[208:211], v[6:9]
	v_mfma_f32_16x16x32_bf16 v[2:5], v[172:175], v[208:211], v[2:5]
	v_mfma_f32_16x16x32_bf16 v[42:45], v[168:171], v[184:187], v[42:45]
	v_mfma_f32_16x16x32_bf16 v[34:37], v[176:179], v[184:187], v[34:37]
	v_mfma_f32_16x16x32_bf16 v[26:29], v[168:171], v[192:195], v[26:29]
	v_mfma_f32_16x16x32_bf16 v[18:21], v[176:179], v[192:195], v[18:21]
	v_mfma_f32_16x16x32_bf16 v[14:17], v[168:171], v[204:207], v[14:17]
	v_mfma_f32_16x16x32_bf16 v[10:13], v[176:179], v[204:207], v[10:13]
	v_mfma_f32_16x16x32_bf16 v[6:9], v[168:171], v[212:215], v[6:9]
	v_mfma_f32_16x16x32_bf16 v[2:5], v[176:179], v[212:215], v[2:5]
	s_setprio 0
	s_barrier
	s_add_i32 s43, s43, 2
	s_add_u32 s8, s8, 0x100
	s_addc_u32 s9, s9, 0
	s_add_u32 s33, s33, 0x100
	s_addc_u32 s42, s42, 0
	s_cmp_gt_u32 s43, 29
	s_cbranch_scc0 .LBB0_262
	s_and_b64 vcc, exec, s[2:3]
	s_cbranch_vccz .LBB0_265
	s_barrier

; #define PG8_STAGE(bufoff, gbase, voff) do { _Pragma("unroll") for (int _i = 0; _i < 2; ++_i) \
;         __builtin_amdgcn_global_load_lds((const unsigned*)((const char*)(gbase) + (voff)[_i]), (LAS unsigned*)(lds + (bufoff) + ldsw + _i * 8192), 16, 0, 0); } while (0)
; #define PG8_LDA(dst, b, h) do { _Pragma("unroll") for (int m = 0; m < 4; ++m) _Pragma("unroll") for (int k = 0; k < 2; ++k) dst[m][k] = *(const LAS bf16x8*)(lds + PG8_SA(b, h) + aoff + m * 2048 + k * 1024); } while (0)
; #define PG8_LDB(dst, b, h) do { _Pragma("unroll") for (int n = 0; n < 2; ++n) _Pragma("unroll") for (int k = 0; k < 2; ++k) dst[n][k] = *(const LAS bf16x8*)(lds + PG8_SB(b, h) + boff + n * 2048 + k * 1024); } while (0)
; #define PG8_MMA(ai, bj, At, Bt) do { __builtin_amdgcn_s_setprio(1); _Pragma("unroll") for (int m = 0; m < 4; ++m) _Pragma("unroll") for (int n = 0; n < 2; ++n) _Pragma("unroll") for (int k = 0; k < 2; ++k) \
;         acc[ai][bj][m][n] = __builtin_amdgcn_mfma_f32_16x16x32_bf16(Bt[n][k], At[m][k], acc[ai][bj][m][n], 0, 0, 0); __builtin_amdgcn_s_setprio(0); } while (0)
; #define PG8_WAIT_V(n) asm volatile("s_waitcnt vmcnt(" #n ")" ::: "memory")
; #define PG8_WAIT_L(n) asm volatile("s_waitcnt lgkmcnt(" #n ")" ::: "memory")
; #define PG8_BAR __builtin_amdgcn_s_barrier()
; #define PG8_SCHED __builtin_amdgcn_sched_barrier(0)
; template <class Epi, class Sched>
; __device__ __forceinline__ void gemm_phase(LAS unsigned char* lds, const int lda, const int ldb, const int K, const Sched& S, const Epi& E, int tid) {
;     ...
;         for (int t = 0; t < nt; t += 2) {
;             const bool last = (t == nt - 2);
;             const char* a1 = cA + (size_t)(t + 1) * kstep;
;             const char* a2 = last ? nA : cA + (size_t)(t + 2) * kstep; const char* b2 = last ? nB : cB + (size_t)(t + 2) * kstep;
;             const char* a3 = a2 + kstep; const char* b3 = b2 + kstep;
;             PG8_LDB(B0, 0, 0); PG8_LDB(B1, 0, 1); PG8_SCHED; PG8_LDA(At, 0, 0); PG8_STAGE(PG8_SA(1, 1), a1 + hA, voffA);
;             PG8_WAIT_V(8); PG8_WAIT_L(0); PG8_BAR; PG8_MMA(0, 0, At, B0); PG8_MMA(0, 1, At, B1); PG8_BAR; PG8_SCHED;
;             PG8_LDA(At, 0, 1); PG8_STAGE(PG8_SB(0, 0), b2, voffB); PG8_STAGE(PG8_SB(0, 1), b2 + hB, voffB); PG8_STAGE(PG8_SA(0, 0), a2, voffA);
;             PG8_WAIT_V(8); PG8_WAIT_L(0); PG8_BAR; PG8_MMA(1, 0, At, B0); PG8_MMA(1, 1, At, B1); PG8_BAR; PG8_SCHED;
.LBB0_290:
	s_add_u32 s14, s10, 0xfff80080
	s_addc_u32 s15, s11, -1
	s_add_i32 s34, 0, 0x10000
	s_cmp_eq_u32 s42, 28
	s_cselect_b32 s17, s5, s15
	s_cselect_b32 s16, s4, s14
	s_cselect_b32 s15, s7, s33
	s_cselect_b32 s14, s6, s18
	s_add_i32 s35, 0, 0x14000
	v_add_u32_e32 v156, s34, v163
	v_add_u32_e32 v160, s35, v163
	ds_read_b128 v[144:147], v156
	ds_read_b128 v[148:151], v156 offset:1024
	ds_read_b128 v[152:155], v156 offset:2048
	ds_read_b128 v[156:159], v156 offset:3072
	ds_read_b128 v[166:169], v160
	ds_read_b128 v[170:173], v160 offset:1024
	ds_read_b128 v[174:177], v160 offset:2048
	ds_read_b128 v[178:181], v160 offset:3072
	s_add_i32 m0, s21, 0xc000
	ds_read_b128 v[182:185], v164
	ds_read_b128 v[186:189], v164 offset:1024
	ds_read_b128 v[190:193], v164 offset:2048
	ds_read_b128 v[194:197], v164 offset:3072
	ds_read_b128 v[200:203], v164 offset:4096
	ds_read_b128 v[204:207], v164 offset:5120
	ds_read_b128 v[208:211], v164 offset:6144
	ds_read_b128 v[212:215], v164 offset:7168
	global_load_lds_dwordx4 v140, s[10:11]
	s_add_i32 m0, s21, 0xe000
	s_nop 0
	global_load_lds_dwordx4 v142, s[10:11]
	s_waitcnt vmcnt(8)
	s_waitcnt lgkmcnt(0)
	s_barrier
	s_setprio 1
	s_waitcnt lgkmcnt(0)
	v_mfma_f32_16x16x32_bf16 v[126:129], v[144:147], v[182:185], v[126:129]
	v_mfma_f32_16x16x32_bf16 v[122:125], v[152:155], v[182:185], v[122:125]
	v_mfma_f32_16x16x32_bf16 v[118:121], v[144:147], v[190:193], v[118:121]
	v_mfma_f32_16x16x32_bf16 v[114:117], v[152:155], v[190:193], v[114:117]
	v_mfma_f32_16x16x32_bf16 v[102:105], v[144:147], v[200:203], v[102:105]
	v_mfma_f32_16x16x32_bf16 v[98:101], v[152:155], v[200:203], v[98:101]
	v_mfma_f32_16x16x32_bf16 v[86:89], v[144:147], v[208:211], v[86:89]
	v_mfma_f32_16x16x32_bf16 v[82:85], v[152:155], v[208:211], v[82:85]
	v_mfma_f32_16x16x32_bf16 v[126:129], v[148:151], v[186:189], v[126:129]
	v_mfma_f32_16x16x32_bf16 v[122:125], v[156:159], v[186:189], v[122:125]
	v_mfma_f32_16x16x32_bf16 v[118:121], v[148:151], v[194:197], v[118:121]
	v_mfma_f32_16x16x32_bf16 v[114:117], v[156:159], v[194:197], v[114:117]
	v_mfma_f32_16x16x32_bf16 v[102:105], v[148:151], v[204:207], v[102:105]
	v_mfma_f32_16x16x32_bf16 v[98:101], v[156:159], v[204:207], v[98:101]
	v_mfma_f32_16x16x32_bf16 v[86:89], v[148:151], v[212:215], v[86:89]
	v_mfma_f32_16x16x32_bf16 v[82:85], v[156:159], v[212:215], v[82:85]
	s_setprio 0
	s_setprio 1
	v_mfma_f32_16x16x32_bf16 v[110:113], v[166:169], v[182:185], v[110:113]
	v_mfma_f32_16x16x32_bf16 v[106:109], v[174:177], v[182:185], v[106:109]
	v_mfma_f32_16x16x32_bf16 v[94:97], v[166:169], v[190:193], v[94:97]
	v_mfma_f32_16x16x32_bf16 v[90:93], v[174:177], v[190:193], v[90:93]
	v_mfma_f32_16x16x32_bf16 v[78:81], v[166:169], v[200:203], v[78:81]
	v_mfma_f32_16x16x32_bf16 v[74:77], v[174:177], v[200:203], v[74:77]
	v_mfma_f32_16x16x32_bf16 v[70:73], v[166:169], v[208:211], v[70:73]
	v_mfma_f32_16x16x32_bf16 v[66:69], v[174:177], v[208:211], v[66:69]
	v_mfma_f32_16x16x32_bf16 v[110:113], v[170:173], v[186:189], v[110:113]
	v_mfma_f32_16x16x32_bf16 v[106:109], v[178:181], v[186:189], v[106:109]
	v_mfma_f32_16x16x32_bf16 v[94:97], v[170:173], v[194:197], v[94:97]
	v_mfma_f32_16x16x32_bf16 v[90:93], v[178:181], v[194:197], v[90:93]
	v_mfma_f32_16x16x32_bf16 v[78:81], v[170:173], v[204:207], v[78:81]
	v_mfma_f32_16x16x32_bf16 v[74:77], v[178:181], v[204:207], v[74:77]
	v_mfma_f32_16x16x32_bf16 v[70:73], v[170:173], v[212:215], v[70:73]
	v_mfma_f32_16x16x32_bf16 v[66:69], v[178:181], v[212:215], v[66:69]
	s_setprio 0
	s_barrier
	s_add_u32 s98, s14, s30
	s_addc_u32 s99, s15, s31
	s_add_u32 s100, s16, s30
	s_addc_u32 s101, s17, s31
	s_add_i32 s34, s34, s20
	s_mov_b32 m0, s34
	ds_read_b128 v[182:185], v164 offset:16384
	ds_read_b128 v[186:189], v164 offset:17408
	ds_read_b128 v[190:193], v164 offset:18432
	ds_read_b128 v[194:197], v164 offset:19456
	ds_read_b128 v[200:203], v164 offset:20480
	ds_read_b128 v[204:207], v164 offset:21504
	ds_read_b128 v[208:211], v164 offset:22528
	ds_read_b128 v[212:215], v164 offset:23552
	global_load_lds_dwordx4 v0, s[14:15]
	s_add_i32 m0, s34, 0x2000
	s_add_u32 s44, s14, 0x80000
	s_addc_u32 s45, s15, 0
	s_add_i32 s34, s35, s20
	global_load_lds_dwordx4 v134, s[14:15]
	s_mov_b32 m0, s34
	s_nop 0
	global_load_lds_dwordx4 v0, s[44:45]
	s_add_i32 m0, s34, 0x2000
	s_nop 0
	global_load_lds_dwordx4 v134, s[44:45]
	s_mov_b32 m0, s21
	s_nop 0
	global_load_lds_dwordx4 v130, s[16:17]
	s_mov_b32 m0, s22
	s_nop 0
	global_load_lds_dwordx4 v132, s[16:17]
	s_waitcnt vmcnt(8)
	s_waitcnt lgkmcnt(0)
	s_barrier
; #define PG8_STAGE(bufoff, gbase, voff) do { _Pragma("unroll") for (int _i = 0; _i < 2; ++_i) \
;         __builtin_amdgcn_global_load_lds((const unsigned*)((const char*)(gbase) + (voff)[_i]), (LAS unsigned*)(lds + (bufoff) + ldsw + _i * 8192), 16, 0, 0); } while (0)
; #define PG8_LDA(dst, b, h) do { _Pragma("unroll") for (int m = 0; m < 4; ++m) _Pragma("unroll") for (int k = 0; k < 2; ++k) dst[m][k] = *(const LAS bf16x8*)(lds + PG8_SA(b, h) + aoff + m * 2048 + k * 1024); } while (0)
; #define PG8_LDB(dst, b, h) do { _Pragma("unroll") for (int n = 0; n < 2; ++n) _Pragma("unroll") for (int k = 0; k < 2; ++k) dst[n][k] = *(const LAS bf16x8*)(lds + PG8_SB(b, h) + boff + n * 2048 + k * 1024); } while (0)
; #define PG8_MMA(ai, bj, At, Bt) do { __builtin_amdgcn_s_setprio(1); _Pragma("unroll") for (int m = 0; m < 4; ++m) _Pragma("unroll") for (int n = 0; n < 2; ++n) _Pragma("unroll") for (int k = 0; k < 2; ++k) \
;         acc[ai][bj][m][n] = __builtin_amdgcn_mfma_f32_16x16x32_bf16(Bt[n][k], At[m][k], acc[ai][bj][m][n], 0, 0, 0); __builtin_amdgcn_s_setprio(0); } while (0)
; #define PG8_WAIT_V(n) asm volatile("s_waitcnt vmcnt(" #n ")" ::: "memory")
; #define PG8_WAIT_L(n) asm volatile("s_waitcnt lgkmcnt(" #n ")" ::: "memory")
; #define PG8_BAR __builtin_amdgcn_s_barrier()
; #define PG8_SCHED __builtin_amdgcn_sched_barrier(0)
; template <class Epi, class Sched>
; __device__ __forceinline__ void gemm_phase(LAS unsigned char* lds, const int lda, const int ldb, const int K, const Sched& S, const Epi& E, int tid) {
;     ...
;             PG8_WAIT_V(8); PG8_WAIT_L(0); PG8_BAR; PG8_MMA(1, 0, At, B0); PG8_MMA(1, 1, At, B1); PG8_BAR; PG8_SCHED;
;             PG8_LDB(B0, 1, 0); PG8_LDB(B1, 1, 1); PG8_SCHED; PG8_LDA(At, 1, 0); PG8_STAGE(PG8_SA(0, 1), a2 + hA, voffA);
;             PG8_WAIT_V(8); PG8_WAIT_L(0); PG8_BAR; PG8_MMA(0, 0, At, B0); PG8_MMA(0, 1, At, B1); PG8_BAR; PG8_SCHED;
	s_setprio 1
	s_waitcnt lgkmcnt(0)
	v_mfma_f32_16x16x32_bf16 v[62:65], v[144:147], v[182:185], v[62:65]
	v_mfma_f32_16x16x32_bf16 v[58:61], v[152:155], v[182:185], v[58:61]
	v_mfma_f32_16x16x32_bf16 v[54:57], v[144:147], v[190:193], v[54:57]
	v_mfma_f32_16x16x32_bf16 v[50:53], v[152:155], v[190:193], v[50:53]
	v_mfma_f32_16x16x32_bf16 v[38:41], v[144:147], v[200:203], v[38:41]
	v_mfma_f32_16x16x32_bf16 v[34:37], v[152:155], v[200:203], v[34:37]
	v_mfma_f32_16x16x32_bf16 v[22:25], v[144:147], v[208:211], v[22:25]
	v_mfma_f32_16x16x32_bf16 v[18:21], v[152:155], v[208:211], v[18:21]
	v_mfma_f32_16x16x32_bf16 v[62:65], v[148:151], v[186:189], v[62:65]
	v_mfma_f32_16x16x32_bf16 v[58:61], v[156:159], v[186:189], v[58:61]
	v_mfma_f32_16x16x32_bf16 v[54:57], v[148:151], v[194:197], v[54:57]
	v_mfma_f32_16x16x32_bf16 v[50:53], v[156:159], v[194:197], v[50:53]
	v_mfma_f32_16x16x32_bf16 v[38:41], v[148:151], v[204:207], v[38:41]
	v_mfma_f32_16x16x32_bf16 v[34:37], v[156:159], v[204:207], v[34:37]
	v_mfma_f32_16x16x32_bf16 v[22:25], v[148:151], v[212:215], v[22:25]
	v_mfma_f32_16x16x32_bf16 v[18:21], v[156:159], v[212:215], v[18:21]
	s_setprio 0
	s_setprio 1
	v_mfma_f32_16x16x32_bf16 v[46:49], v[166:169], v[182:185], v[46:49]
	v_mfma_f32_16x16x32_bf16 v[42:45], v[174:177], v[182:185], v[42:45]
	v_mfma_f32_16x16x32_bf16 v[30:33], v[166:169], v[190:193], v[30:33]
	v_mfma_f32_16x16x32_bf16 v[26:29], v[174:177], v[190:193], v[26:29]
	v_mfma_f32_16x16x32_bf16 v[14:17], v[166:169], v[200:203], v[14:17]
	v_mfma_f32_16x16x32_bf16 v[10:13], v[174:177], v[200:203], v[10:13]
	v_mfma_f32_16x16x32_bf16 v[6:9], v[166:169], v[208:211], v[6:9]
	v_mfma_f32_16x16x32_bf16 v[2:5], v[174:177], v[208:211], v[2:5]
	v_mfma_f32_16x16x32_bf16 v[46:49], v[170:173], v[186:189], v[46:49]
	v_mfma_f32_16x16x32_bf16 v[42:45], v[178:181], v[186:189], v[42:45]
	v_mfma_f32_16x16x32_bf16 v[30:33], v[170:173], v[194:197], v[30:33]
	v_mfma_f32_16x16x32_bf16 v[26:29], v[178:181], v[194:197], v[26:29]
	v_mfma_f32_16x16x32_bf16 v[14:17], v[170:173], v[204:207], v[14:17]
	v_mfma_f32_16x16x32_bf16 v[10:13], v[178:181], v[204:207], v[10:13]
	v_mfma_f32_16x16x32_bf16 v[6:9], v[170:173], v[212:215], v[6:9]
	v_mfma_f32_16x16x32_bf16 v[2:5], v[178:181], v[212:215], v[2:5]
	s_setprio 0
	s_barrier
	s_add_i32 s34, 0, 0x18000
	s_add_i32 s35, 0, 0x1c000
	v_add_u32_e32 v156, s34, v163
	v_add_u32_e32 v165, s35, v163
	ds_read_b128 v[144:147], v156
	ds_read_b128 v[148:151], v156 offset:1024
	ds_read_b128 v[152:155], v156 offset:2048
	ds_read_b128 v[156:159], v156 offset:3072
	ds_read_b128 v[166:169], v165
	ds_read_b128 v[170:173], v165 offset:1024
	ds_read_b128 v[174:177], v165 offset:2048
	ds_read_b128 v[178:181], v165 offset:3072
	s_add_u32 s16, s16, 0x80000
	s_addc_u32 s17, s17, 0
	s_mov_b32 m0, s23
	ds_read_b128 v[182:185], v164 offset:32768
	ds_read_b128 v[186:189], v164 offset:33792
	ds_read_b128 v[190:193], v164 offset:34816
	ds_read_b128 v[194:197], v164 offset:35840
	ds_read_b128 v[200:203], v164 offset:36864
	ds_read_b128 v[204:207], v164 offset:37888
	ds_read_b128 v[208:211], v164 offset:38912
	ds_read_b128 v[212:215], v164 offset:39936
	global_load_lds_dwordx4 v130, s[16:17]
	s_mov_b32 m0, s25
	s_nop 0
	global_load_lds_dwordx4 v132, s[16:17]
	s_waitcnt vmcnt(8)
	s_waitcnt lgkmcnt(0)
	s_barrier
	s_setprio 1
	s_waitcnt lgkmcnt(0)
	v_mfma_f32_16x16x32_bf16 v[126:129], v[144:147], v[182:185], v[126:129]
	v_mfma_f32_16x16x32_bf16 v[122:125], v[152:155], v[182:185], v[122:125]
	v_mfma_f32_16x16x32_bf16 v[118:121], v[144:147], v[190:193], v[118:121]
	v_mfma_f32_16x16x32_bf16 v[114:117], v[152:155], v[190:193], v[114:117]
	v_mfma_f32_16x16x32_bf16 v[102:105], v[144:147], v[200:203], v[102:105]
	v_mfma_f32_16x16x32_bf16 v[98:101], v[152:155], v[200:203], v[98:101]
	v_mfma_f32_16x16x32_bf16 v[86:89], v[144:147], v[208:211], v[86:89]
	v_mfma_f32_16x16x32_bf16 v[82:85], v[152:155], v[208:211], v[82:85]
	v_mfma_f32_16x16x32_bf16 v[126:129], v[148:151], v[186:189], v[126:129]
	v_mfma_f32_16x16x32_bf16 v[122:125], v[156:159], v[186:189], v[122:125]
	v_mfma_f32_16x16x32_bf16 v[118:121], v[148:151], v[194:197], v[118:121]
	v_mfma_f32_16x16x32_bf16 v[114:117], v[156:159], v[194:197], v[114:117]
	v_mfma_f32_16x16x32_bf16 v[102:105], v[148:151], v[204:207], v[102:105]
	v_mfma_f32_16x16x32_bf16 v[98:101], v[156:159], v[204:207], v[98:101]
	v_mfma_f32_16x16x32_bf16 v[86:89], v[148:151], v[212:215], v[86:89]
	v_mfma_f32_16x16x32_bf16 v[82:85], v[156:159], v[212:215], v[82:85]
	s_setprio 0
	s_setprio 1
	v_mfma_f32_16x16x32_bf16 v[110:113], v[166:169], v[182:185], v[110:113]
	v_mfma_f32_16x16x32_bf16 v[106:109], v[174:177], v[182:185], v[106:109]
	v_mfma_f32_16x16x32_bf16 v[94:97], v[166:169], v[190:193], v[94:97]
	v_mfma_f32_16x16x32_bf16 v[90:93], v[174:177], v[190:193], v[90:93]
	v_mfma_f32_16x16x32_bf16 v[78:81], v[166:169], v[200:203], v[78:81]
	v_mfma_f32_16x16x32_bf16 v[74:77], v[174:177], v[200:203], v[74:77]
	v_mfma_f32_16x16x32_bf16 v[70:73], v[166:169], v[208:211], v[70:73]
	v_mfma_f32_16x16x32_bf16 v[66:69], v[174:177], v[208:211], v[66:69]
	v_mfma_f32_16x16x32_bf16 v[110:113], v[170:173], v[186:189], v[110:113]
	v_mfma_f32_16x16x32_bf16 v[106:109], v[178:181], v[186:189], v[106:109]
	v_mfma_f32_16x16x32_bf16 v[94:97], v[170:173], v[194:197], v[94:97]
	v_mfma_f32_16x16x32_bf16 v[90:93], v[178:181], v[194:197], v[90:93]
	v_mfma_f32_16x16x32_bf16 v[78:81], v[170:173], v[204:207], v[78:81]
	v_mfma_f32_16x16x32_bf16 v[74:77], v[178:181], v[204:207], v[74:77]
	v_mfma_f32_16x16x32_bf16 v[70:73], v[170:173], v[212:215], v[70:73]
	v_mfma_f32_16x16x32_bf16 v[66:69], v[178:181], v[212:215], v[66:69]
	s_setprio 0
	s_barrier
; #define PG8_STAGE(bufoff, gbase, voff) do { _Pragma("unroll") for (int _i = 0; _i < 2; ++_i) \
;         __builtin_amdgcn_global_load_lds((const unsigned*)((const char*)(gbase) + (voff)[_i]), (LAS unsigned*)(lds + (bufoff) + ldsw + _i * 8192), 16, 0, 0); } while (0)
; #define PG8_LDA(dst, b, h) do { _Pragma("unroll") for (int m = 0; m < 4; ++m) _Pragma("unroll") for (int k = 0; k < 2; ++k) dst[m][k] = *(const LAS bf16x8*)(lds + PG8_SA(b, h) + aoff + m * 2048 + k * 1024); } while (0)
; #define PG8_MMA(ai, bj, At, Bt) do { __builtin_amdgcn_s_setprio(1); _Pragma("unroll") for (int m = 0; m < 4; ++m) _Pragma("unroll") for (int n = 0; n < 2; ++n) _Pragma("unroll") for (int k = 0; k < 2; ++k) \
;         acc[ai][bj][m][n] = __builtin_amdgcn_mfma_f32_16x16x32_bf16(Bt[n][k], At[m][k], acc[ai][bj][m][n], 0, 0, 0); __builtin_amdgcn_s_setprio(0); } while (0)
; #define PG8_WAIT_V(n) asm volatile("s_waitcnt vmcnt(" #n ")" ::: "memory")
; #define PG8_WAIT_L(n) asm volatile("s_waitcnt lgkmcnt(" #n ")" ::: "memory")
; #define PG8_BAR __builtin_amdgcn_s_barrier()
; #define PG8_SCHED __builtin_amdgcn_sched_barrier(0)
; template <class Epi, class Sched>
; __device__ __forceinline__ void gemm_phase(LAS unsigned char* lds, const int lda, const int ldb, const int K, const Sched& S, const Epi& E, int tid) {
;     ...
;             PG8_LDA(At, 1, 1); PG8_STAGE(PG8_SB(1, 0), b3, voffB); PG8_STAGE(PG8_SB(1, 1), b3 + hB, voffB); PG8_STAGE(PG8_SA(1, 0), a3, voffA);
;             PG8_WAIT_V(8); PG8_WAIT_L(0); PG8_BAR; PG8_MMA(1, 0, At, B0); PG8_MMA(1, 1, At, B1); PG8_BAR; PG8_SCHED;
;         }
	s_add_i32 s16, s34, s20
	s_mov_b32 m0, s16
	ds_read_b128 v[182:185], v164 offset:49152
	ds_read_b128 v[186:189], v164 offset:50176
	ds_read_b128 v[190:193], v164 offset:51200
	ds_read_b128 v[194:197], v164 offset:52224
	ds_read_b128 v[200:203], v164 offset:53248
	ds_read_b128 v[204:207], v164 offset:54272
	ds_read_b128 v[208:211], v164 offset:55296
	ds_read_b128 v[212:215], v164 offset:56320
	global_load_lds_dwordx4 v0, s[98:99]
	s_add_i32 m0, s16, 0x2000
	s_add_u32 s14, s14, 0x80080
	s_addc_u32 s15, s15, 0
	s_add_i32 s16, s35, s20
	global_load_lds_dwordx4 v134, s[98:99]
	s_mov_b32 m0, s16
	s_nop 0
	global_load_lds_dwordx4 v0, s[14:15]
	s_add_i32 m0, s16, 0x2000
	s_nop 0
	global_load_lds_dwordx4 v134, s[14:15]
	s_mov_b32 m0, s26
	s_nop 0
	global_load_lds_dwordx4 v130, s[100:101]
	s_mov_b32 m0, s27
	s_nop 0
	global_load_lds_dwordx4 v132, s[100:101]
	s_waitcnt vmcnt(8)
	s_waitcnt lgkmcnt(0)
	s_barrier
	s_setprio 1
	s_waitcnt lgkmcnt(0)
	v_mfma_f32_16x16x32_bf16 v[62:65], v[144:147], v[182:185], v[62:65]
	v_mfma_f32_16x16x32_bf16 v[58:61], v[152:155], v[182:185], v[58:61]
	v_mfma_f32_16x16x32_bf16 v[54:57], v[144:147], v[190:193], v[54:57]
	v_mfma_f32_16x16x32_bf16 v[50:53], v[152:155], v[190:193], v[50:53]
	v_mfma_f32_16x16x32_bf16 v[38:41], v[144:147], v[200:203], v[38:41]
	v_mfma_f32_16x16x32_bf16 v[34:37], v[152:155], v[200:203], v[34:37]
	v_mfma_f32_16x16x32_bf16 v[22:25], v[144:147], v[208:211], v[22:25]
	v_mfma_f32_16x16x32_bf16 v[18:21], v[152:155], v[208:211], v[18:21]
	v_mfma_f32_16x16x32_bf16 v[62:65], v[148:151], v[186:189], v[62:65]
	v_mfma_f32_16x16x32_bf16 v[58:61], v[156:159], v[186:189], v[58:61]
	v_mfma_f32_16x16x32_bf16 v[54:57], v[148:151], v[194:197], v[54:57]
	v_mfma_f32_16x16x32_bf16 v[50:53], v[156:159], v[194:197], v[50:53]
	v_mfma_f32_16x16x32_bf16 v[38:41], v[148:151], v[204:207], v[38:41]
	v_mfma_f32_16x16x32_bf16 v[34:37], v[156:159], v[204:207], v[34:37]
	v_mfma_f32_16x16x32_bf16 v[22:25], v[148:151], v[212:215], v[22:25]
	v_mfma_f32_16x16x32_bf16 v[18:21], v[156:159], v[212:215], v[18:21]
	s_setprio 0
	s_setprio 1
	v_mfma_f32_16x16x32_bf16 v[46:49], v[166:169], v[182:185], v[46:49]
	v_mfma_f32_16x16x32_bf16 v[42:45], v[174:177], v[182:185], v[42:45]
	v_mfma_f32_16x16x32_bf16 v[30:33], v[166:169], v[190:193], v[30:33]
	v_mfma_f32_16x16x32_bf16 v[26:29], v[174:177], v[190:193], v[26:29]
	v_mfma_f32_16x16x32_bf16 v[14:17], v[166:169], v[200:203], v[14:17]
	v_mfma_f32_16x16x32_bf16 v[10:13], v[174:177], v[200:203], v[10:13]
	v_mfma_f32_16x16x32_bf16 v[6:9], v[166:169], v[208:211], v[6:9]
	v_mfma_f32_16x16x32_bf16 v[2:5], v[174:177], v[208:211], v[2:5]
	v_mfma_f32_16x16x32_bf16 v[46:49], v[170:173], v[186:189], v[46:49]
	v_mfma_f32_16x16x32_bf16 v[42:45], v[178:181], v[186:189], v[42:45]
	v_mfma_f32_16x16x32_bf16 v[30:33], v[170:173], v[194:197], v[30:33]
	v_mfma_f32_16x16x32_bf16 v[26:29], v[178:181], v[194:197], v[26:29]
	v_mfma_f32_16x16x32_bf16 v[14:17], v[170:173], v[204:207], v[14:17]
	v_mfma_f32_16x16x32_bf16 v[10:13], v[178:181], v[204:207], v[10:13]
	v_mfma_f32_16x16x32_bf16 v[6:9], v[170:173], v[212:215], v[6:9]
	v_mfma_f32_16x16x32_bf16 v[2:5], v[178:181], v[212:215], v[2:5]
	s_setprio 0
	s_barrier
	s_add_i32 s42, s42, 2
	s_add_u32 s10, s10, 0x100
	s_addc_u32 s11, s11, 0
	s_add_u32 s18, s18, 0x100
	s_addc_u32 s33, s33, 0
	s_cmp_gt_u32 s42, 29
	s_cbranch_scc0 .LBB0_290
	s_and_b64 vcc, exec, s[2:3]
	s_cbranch_vccz .LBB0_293
	s_barrier

; #define PG8_STAGE(bufoff, gbase, voff) do { _Pragma("unroll") for (int _i = 0; _i < 2; ++_i) \
;         __builtin_amdgcn_global_load_lds((const unsigned*)((const char*)(gbase) + (voff)[_i]), (LAS unsigned*)(lds + (bufoff) + ldsw + _i * 8192), 16, 0, 0); } while (0)
; #define PG8_LDA(dst, b, h) do { _Pragma("unroll") for (int m = 0; m < 4; ++m) _Pragma("unroll") for (int k = 0; k < 2; ++k) dst[m][k] = *(const LAS bf16x8*)(lds + PG8_SA(b, h) + aoff + m * 2048 + k * 1024); } while (0)
; #define PG8_LDB(dst, b, h) do { _Pragma("unroll") for (int n = 0; n < 2; ++n) _Pragma("unroll") for (int k = 0; k < 2; ++k) dst[n][k] = *(const LAS bf16x8*)(lds + PG8_SB(b, h) + boff + n * 2048 + k * 1024); } while (0)
; #define PG8_MMA(ai, bj, At, Bt) do { __builtin_amdgcn_s_setprio(1); _Pragma("unroll") for (int m = 0; m < 4; ++m) _Pragma("unroll") for (int n = 0; n < 2; ++n) _Pragma("unroll") for (int k = 0; k < 2; ++k) \
;         acc[ai][bj][m][n] = __builtin_amdgcn_mfma_f32_16x16x32_bf16(Bt[n][k], At[m][k], acc[ai][bj][m][n], 0, 0, 0); __builtin_amdgcn_s_setprio(0); } while (0)
; #define PG8_WAIT_V(n) asm volatile("s_waitcnt vmcnt(" #n ")" ::: "memory")
; #define PG8_WAIT_L(n) asm volatile("s_waitcnt lgkmcnt(" #n ")" ::: "memory")
; #define PG8_BAR __builtin_amdgcn_s_barrier()
; #define PG8_SCHED __builtin_amdgcn_sched_barrier(0)
; template <class Epi, class Sched>
; __device__ __forceinline__ void gemm_phase(LAS unsigned char* lds, const int lda, const int ldb, const int K, const Sched& S, const Epi& E, int tid) {
;     ...
;         for (int t = 0; t < nt; t += 2) {
;             const bool last = (t == nt - 2);
;             const char* a1 = cA + (size_t)(t + 1) * kstep;
;             const char* a2 = last ? nA : cA + (size_t)(t + 2) * kstep; const char* b2 = last ? nB : cB + (size_t)(t + 2) * kstep;
;             const char* a3 = a2 + kstep; const char* b3 = b2 + kstep;
;             PG8_LDB(B0, 0, 0); PG8_LDB(B1, 0, 1); PG8_SCHED; PG8_LDA(At, 0, 0); PG8_STAGE(PG8_SA(1, 1), a1 + hA, voffA);
;             PG8_WAIT_V(8); PG8_WAIT_L(0); PG8_BAR; PG8_MMA(0, 0, At, B0); PG8_MMA(0, 1, At, B1); PG8_BAR; PG8_SCHED;
;             PG8_LDA(At, 0, 1); PG8_STAGE(PG8_SB(0, 0), b2, voffB); PG8_STAGE(PG8_SB(0, 1), b2 + hB, voffB); PG8_STAGE(PG8_SA(0, 0), a2, voffA);
;             PG8_WAIT_V(8); PG8_WAIT_L(0); PG8_BAR; PG8_MMA(1, 0, At, B0); PG8_MMA(1, 1, At, B1); PG8_BAR; PG8_SCHED;
.LBB0_448:
	s_add_u32 s10, s8, 0x100
	s_addc_u32 s11, s9, 0
	s_add_i32 s34, 0, 0x10000
	s_cmp_eq_u32 s44, 2
	s_cselect_b32 s17, s5, s11
	s_cselect_b32 s16, s4, s10
	s_cselect_b32 s15, s7, s43
	s_cselect_b32 s14, s6, s42
	s_add_i32 s35, 0, 0x14000
	v_add_u32_e32 v152, s34, v157
	v_add_u32_e32 v172, s35, v157
	ds_read_b128 v[130:133], v152
	ds_read_b128 v[134:137], v152 offset:1024
	ds_read_b128 v[148:151], v152 offset:2048
	ds_read_b128 v[152:155], v152 offset:3072
	ds_read_b128 v[160:163], v172
	ds_read_b128 v[164:167], v172 offset:1024
	ds_read_b128 v[168:171], v172 offset:2048
	ds_read_b128 v[172:175], v172 offset:3072
	s_add_i32 m0, s19, 0xc000
	ds_read_b128 v[176:179], v159
	ds_read_b128 v[180:183], v159 offset:1024
	ds_read_b128 v[184:187], v159 offset:2048
	ds_read_b128 v[188:191], v159 offset:3072
	ds_read_b128 v[192:195], v159 offset:4096
	ds_read_b128 v[200:203], v159 offset:5120
	ds_read_b128 v[204:207], v159 offset:6144
	ds_read_b128 v[208:211], v159 offset:7168
	global_load_lds_dwordx4 v144, s[8:9]
	s_add_i32 m0, s19, 0xe000
	s_nop 0
	global_load_lds_dwordx4 v146, s[8:9]
	s_waitcnt vmcnt(8)
	s_waitcnt lgkmcnt(0)
	s_barrier
	s_setprio 1
	s_waitcnt lgkmcnt(0)
	v_mfma_f32_16x16x32_bf16 v[126:129], v[130:133], v[176:179], v[126:129]
	v_mfma_f32_16x16x32_bf16 v[122:125], v[148:151], v[176:179], v[122:125]
	v_mfma_f32_16x16x32_bf16 v[118:121], v[130:133], v[184:187], v[118:121]
	v_mfma_f32_16x16x32_bf16 v[114:117], v[148:151], v[184:187], v[114:117]
	v_mfma_f32_16x16x32_bf16 v[110:113], v[130:133], v[192:195], v[110:113]
	v_mfma_f32_16x16x32_bf16 v[106:109], v[148:151], v[192:195], v[106:109]
	v_mfma_f32_16x16x32_bf16 v[102:105], v[130:133], v[204:207], v[102:105]
	v_mfma_f32_16x16x32_bf16 v[98:101], v[148:151], v[204:207], v[98:101]
	v_mfma_f32_16x16x32_bf16 v[126:129], v[134:137], v[180:183], v[126:129]
	v_mfma_f32_16x16x32_bf16 v[122:125], v[152:155], v[180:183], v[122:125]
	v_mfma_f32_16x16x32_bf16 v[118:121], v[134:137], v[188:191], v[118:121]
	v_mfma_f32_16x16x32_bf16 v[114:117], v[152:155], v[188:191], v[114:117]
	v_mfma_f32_16x16x32_bf16 v[110:113], v[134:137], v[200:203], v[110:113]
	v_mfma_f32_16x16x32_bf16 v[106:109], v[152:155], v[200:203], v[106:109]
	v_mfma_f32_16x16x32_bf16 v[102:105], v[134:137], v[208:211], v[102:105]
	v_mfma_f32_16x16x32_bf16 v[98:101], v[152:155], v[208:211], v[98:101]
	s_setprio 0
	s_setprio 1
	v_mfma_f32_16x16x32_bf16 v[74:77], v[160:163], v[176:179], v[74:77]
	v_mfma_f32_16x16x32_bf16 v[66:69], v[168:171], v[176:179], v[66:69]
	v_mfma_f32_16x16x32_bf16 v[54:57], v[160:163], v[184:187], v[54:57]
	v_mfma_f32_16x16x32_bf16 v[50:53], v[168:171], v[184:187], v[50:53]
	v_mfma_f32_16x16x32_bf16 v[46:49], v[160:163], v[192:195], v[46:49]
	v_mfma_f32_16x16x32_bf16 v[42:45], v[168:171], v[192:195], v[42:45]
	v_mfma_f32_16x16x32_bf16 v[38:41], v[160:163], v[204:207], v[38:41]
	v_mfma_f32_16x16x32_bf16 v[34:37], v[168:171], v[204:207], v[34:37]
	v_mfma_f32_16x16x32_bf16 v[74:77], v[164:167], v[180:183], v[74:77]
	v_mfma_f32_16x16x32_bf16 v[66:69], v[172:175], v[180:183], v[66:69]
	v_mfma_f32_16x16x32_bf16 v[54:57], v[164:167], v[188:191], v[54:57]
	v_mfma_f32_16x16x32_bf16 v[50:53], v[172:175], v[188:191], v[50:53]
	v_mfma_f32_16x16x32_bf16 v[46:49], v[164:167], v[200:203], v[46:49]
	v_mfma_f32_16x16x32_bf16 v[42:45], v[172:175], v[200:203], v[42:45]
	v_mfma_f32_16x16x32_bf16 v[38:41], v[164:167], v[208:211], v[38:41]
	v_mfma_f32_16x16x32_bf16 v[34:37], v[172:175], v[208:211], v[34:37]
	s_setprio 0
	s_barrier
	s_add_u32 s98, s14, s30
	s_addc_u32 s99, s15, s31
	s_add_u32 s100, s16, s30
	s_addc_u32 s101, s17, s31
	s_add_i32 s8, s34, s18
	s_mov_b32 m0, s8
	ds_read_b128 v[176:179], v159 offset:16384
	ds_read_b128 v[180:183], v159 offset:17408
	ds_read_b128 v[184:187], v159 offset:18432
	ds_read_b128 v[188:191], v159 offset:19456
	ds_read_b128 v[192:195], v159 offset:20480
	ds_read_b128 v[200:203], v159 offset:21504
	ds_read_b128 v[204:207], v159 offset:22528
	ds_read_b128 v[208:211], v159 offset:23552
	global_load_lds_dwordx4 v0, s[14:15]
	s_add_i32 m0, s8, 0x2000
	s_add_u32 s8, s14, 0x18000
	s_addc_u32 s9, s15, 0
	s_add_i32 s34, s35, s18
	global_load_lds_dwordx4 v142, s[14:15]
	s_mov_b32 m0, s34
	s_nop 0
	global_load_lds_dwordx4 v0, s[8:9]
	s_add_i32 m0, s34, 0x2000
	s_nop 0
	global_load_lds_dwordx4 v142, s[8:9]
	s_mov_b32 m0, s19
	s_nop 0
	global_load_lds_dwordx4 v138, s[16:17]
	s_mov_b32 m0, s20
	s_nop 0
	global_load_lds_dwordx4 v140, s[16:17]
	s_waitcnt vmcnt(8)
	s_waitcnt lgkmcnt(0)
	s_barrier
; #define PG8_STAGE(bufoff, gbase, voff) do { _Pragma("unroll") for (int _i = 0; _i < 2; ++_i) \
;         __builtin_amdgcn_global_load_lds((const unsigned*)((const char*)(gbase) + (voff)[_i]), (LAS unsigned*)(lds + (bufoff) + ldsw + _i * 8192), 16, 0, 0); } while (0)
; #define PG8_LDA(dst, b, h) do { _Pragma("unroll") for (int m = 0; m < 4; ++m) _Pragma("unroll") for (int k = 0; k < 2; ++k) dst[m][k] = *(const LAS bf16x8*)(lds + PG8_SA(b, h) + aoff + m * 2048 + k * 1024); } while (0)
; #define PG8_LDB(dst, b, h) do { _Pragma("unroll") for (int n = 0; n < 2; ++n) _Pragma("unroll") for (int k = 0; k < 2; ++k) dst[n][k] = *(const LAS bf16x8*)(lds + PG8_SB(b, h) + boff + n * 2048 + k * 1024); } while (0)
; #define PG8_MMA(ai, bj, At, Bt) do { __builtin_amdgcn_s_setprio(1); _Pragma("unroll") for (int m = 0; m < 4; ++m) _Pragma("unroll") for (int n = 0; n < 2; ++n) _Pragma("unroll") for (int k = 0; k < 2; ++k) \
;         acc[ai][bj][m][n] = __builtin_amdgcn_mfma_f32_16x16x32_bf16(Bt[n][k], At[m][k], acc[ai][bj][m][n], 0, 0, 0); __builtin_amdgcn_s_setprio(0); } while (0)
; #define PG8_WAIT_V(n) asm volatile("s_waitcnt vmcnt(" #n ")" ::: "memory")
; #define PG8_WAIT_L(n) asm volatile("s_waitcnt lgkmcnt(" #n ")" ::: "memory")
; #define PG8_BAR __builtin_amdgcn_s_barrier()
; #define PG8_SCHED __builtin_amdgcn_sched_barrier(0)
; template <class Epi, class Sched>
; __device__ __forceinline__ void gemm_phase(LAS unsigned char* lds, const int lda, const int ldb, const int K, const Sched& S, const Epi& E, int tid) {
;     ...
;             PG8_WAIT_V(8); PG8_WAIT_L(0); PG8_BAR; PG8_MMA(1, 0, At, B0); PG8_MMA(1, 1, At, B1); PG8_BAR; PG8_SCHED;
;             PG8_LDB(B0, 1, 0); PG8_LDB(B1, 1, 1); PG8_SCHED; PG8_LDA(At, 1, 0); PG8_STAGE(PG8_SA(0, 1), a2 + hA, voffA);
;             PG8_WAIT_V(8); PG8_WAIT_L(0); PG8_BAR; PG8_MMA(0, 0, At, B0); PG8_MMA(0, 1, At, B1); PG8_BAR; PG8_SCHED;
	s_setprio 1
	s_waitcnt lgkmcnt(0)
	v_mfma_f32_16x16x32_bf16 v[94:97], v[130:133], v[176:179], v[94:97]
	v_mfma_f32_16x16x32_bf16 v[90:93], v[148:151], v[176:179], v[90:93]
	v_mfma_f32_16x16x32_bf16 v[86:89], v[130:133], v[184:187], v[86:89]
	v_mfma_f32_16x16x32_bf16 v[82:85], v[148:151], v[184:187], v[82:85]
	v_mfma_f32_16x16x32_bf16 v[78:81], v[130:133], v[192:195], v[78:81]
	v_mfma_f32_16x16x32_bf16 v[70:73], v[148:151], v[192:195], v[70:73]
	v_mfma_f32_16x16x32_bf16 v[62:65], v[130:133], v[204:207], v[62:65]
	v_mfma_f32_16x16x32_bf16 v[58:61], v[148:151], v[204:207], v[58:61]
	v_mfma_f32_16x16x32_bf16 v[94:97], v[134:137], v[180:183], v[94:97]
	v_mfma_f32_16x16x32_bf16 v[90:93], v[152:155], v[180:183], v[90:93]
	v_mfma_f32_16x16x32_bf16 v[86:89], v[134:137], v[188:191], v[86:89]
	v_mfma_f32_16x16x32_bf16 v[82:85], v[152:155], v[188:191], v[82:85]
	v_mfma_f32_16x16x32_bf16 v[78:81], v[134:137], v[200:203], v[78:81]
	v_mfma_f32_16x16x32_bf16 v[70:73], v[152:155], v[200:203], v[70:73]
	v_mfma_f32_16x16x32_bf16 v[62:65], v[134:137], v[208:211], v[62:65]
	v_mfma_f32_16x16x32_bf16 v[58:61], v[152:155], v[208:211], v[58:61]
	s_setprio 0
	s_setprio 1
	v_mfma_f32_16x16x32_bf16 v[30:33], v[160:163], v[176:179], v[30:33]
	v_mfma_f32_16x16x32_bf16 v[26:29], v[168:171], v[176:179], v[26:29]
	v_mfma_f32_16x16x32_bf16 v[22:25], v[160:163], v[184:187], v[22:25]
	v_mfma_f32_16x16x32_bf16 v[18:21], v[168:171], v[184:187], v[18:21]
	v_mfma_f32_16x16x32_bf16 v[14:17], v[160:163], v[192:195], v[14:17]
	v_mfma_f32_16x16x32_bf16 v[10:13], v[168:171], v[192:195], v[10:13]
	v_mfma_f32_16x16x32_bf16 v[6:9], v[160:163], v[204:207], v[6:9]
	v_mfma_f32_16x16x32_bf16 v[2:5], v[168:171], v[204:207], v[2:5]
	v_mfma_f32_16x16x32_bf16 v[30:33], v[164:167], v[180:183], v[30:33]
	v_mfma_f32_16x16x32_bf16 v[26:29], v[172:175], v[180:183], v[26:29]
	v_mfma_f32_16x16x32_bf16 v[22:25], v[164:167], v[188:191], v[22:25]
	v_mfma_f32_16x16x32_bf16 v[18:21], v[172:175], v[188:191], v[18:21]
	v_mfma_f32_16x16x32_bf16 v[14:17], v[164:167], v[200:203], v[14:17]
	v_mfma_f32_16x16x32_bf16 v[10:13], v[172:175], v[200:203], v[10:13]
	v_mfma_f32_16x16x32_bf16 v[6:9], v[164:167], v[208:211], v[6:9]
	v_mfma_f32_16x16x32_bf16 v[2:5], v[172:175], v[208:211], v[2:5]
	s_setprio 0
	s_barrier
	s_add_i32 s34, 0, 0x18000
	s_add_i32 s35, 0, 0x1c000
	v_add_u32_e32 v152, s34, v157
	v_add_u32_e32 v172, s35, v157
	ds_read_b128 v[130:133], v152
	ds_read_b128 v[134:137], v152 offset:1024
	ds_read_b128 v[148:151], v152 offset:2048
	ds_read_b128 v[152:155], v152 offset:3072
	ds_read_b128 v[160:163], v172
	ds_read_b128 v[164:167], v172 offset:1024
	ds_read_b128 v[168:171], v172 offset:2048
	ds_read_b128 v[172:175], v172 offset:3072
	s_add_u32 s8, s16, 0x60000
	s_addc_u32 s9, s17, 0
	s_mov_b32 m0, s21
	ds_read_b128 v[176:179], v159 offset:32768
	ds_read_b128 v[180:183], v159 offset:33792
	ds_read_b128 v[184:187], v159 offset:34816
	ds_read_b128 v[188:191], v159 offset:35840
	ds_read_b128 v[192:195], v159 offset:36864
	ds_read_b128 v[200:203], v159 offset:37888
	ds_read_b128 v[204:207], v159 offset:38912
	ds_read_b128 v[208:211], v159 offset:39936
	global_load_lds_dwordx4 v138, s[8:9]
	s_mov_b32 m0, s22
	s_nop 0
	global_load_lds_dwordx4 v140, s[8:9]
	s_waitcnt vmcnt(8)
	s_waitcnt lgkmcnt(0)
	s_barrier
	s_setprio 1
	s_waitcnt lgkmcnt(0)
	v_mfma_f32_16x16x32_bf16 v[126:129], v[130:133], v[176:179], v[126:129]
	v_mfma_f32_16x16x32_bf16 v[122:125], v[148:151], v[176:179], v[122:125]
	v_mfma_f32_16x16x32_bf16 v[118:121], v[130:133], v[184:187], v[118:121]
	v_mfma_f32_16x16x32_bf16 v[114:117], v[148:151], v[184:187], v[114:117]
	v_mfma_f32_16x16x32_bf16 v[110:113], v[130:133], v[192:195], v[110:113]
	v_mfma_f32_16x16x32_bf16 v[106:109], v[148:151], v[192:195], v[106:109]
	v_mfma_f32_16x16x32_bf16 v[102:105], v[130:133], v[204:207], v[102:105]
	v_mfma_f32_16x16x32_bf16 v[98:101], v[148:151], v[204:207], v[98:101]
	v_mfma_f32_16x16x32_bf16 v[126:129], v[134:137], v[180:183], v[126:129]
	v_mfma_f32_16x16x32_bf16 v[122:125], v[152:155], v[180:183], v[122:125]
	v_mfma_f32_16x16x32_bf16 v[118:121], v[134:137], v[188:191], v[118:121]
	v_mfma_f32_16x16x32_bf16 v[114:117], v[152:155], v[188:191], v[114:117]
	v_mfma_f32_16x16x32_bf16 v[110:113], v[134:137], v[200:203], v[110:113]
	v_mfma_f32_16x16x32_bf16 v[106:109], v[152:155], v[200:203], v[106:109]
	v_mfma_f32_16x16x32_bf16 v[102:105], v[134:137], v[208:211], v[102:105]
	v_mfma_f32_16x16x32_bf16 v[98:101], v[152:155], v[208:211], v[98:101]
	s_setprio 0
	s_setprio 1
	v_mfma_f32_16x16x32_bf16 v[74:77], v[160:163], v[176:179], v[74:77]
	v_mfma_f32_16x16x32_bf16 v[66:69], v[168:171], v[176:179], v[66:69]
	v_mfma_f32_16x16x32_bf16 v[54:57], v[160:163], v[184:187], v[54:57]
	v_mfma_f32_16x16x32_bf16 v[50:53], v[168:171], v[184:187], v[50:53]
	v_mfma_f32_16x16x32_bf16 v[46:49], v[160:163], v[192:195], v[46:49]
	v_mfma_f32_16x16x32_bf16 v[42:45], v[168:171], v[192:195], v[42:45]
	v_mfma_f32_16x16x32_bf16 v[38:41], v[160:163], v[204:207], v[38:41]
	v_mfma_f32_16x16x32_bf16 v[34:37], v[168:171], v[204:207], v[34:37]
	v_mfma_f32_16x16x32_bf16 v[74:77], v[164:167], v[180:183], v[74:77]
	v_mfma_f32_16x16x32_bf16 v[66:69], v[172:175], v[180:183], v[66:69]
	v_mfma_f32_16x16x32_bf16 v[54:57], v[164:167], v[188:191], v[54:57]
	v_mfma_f32_16x16x32_bf16 v[50:53], v[172:175], v[188:191], v[50:53]
	v_mfma_f32_16x16x32_bf16 v[46:49], v[164:167], v[200:203], v[46:49]
	v_mfma_f32_16x16x32_bf16 v[42:45], v[172:175], v[200:203], v[42:45]
	v_mfma_f32_16x16x32_bf16 v[38:41], v[164:167], v[208:211], v[38:41]
	v_mfma_f32_16x16x32_bf16 v[34:37], v[172:175], v[208:211], v[34:37]
	s_setprio 0
	s_barrier
; #define PG8_STAGE(bufoff, gbase, voff) do { _Pragma("unroll") for (int _i = 0; _i < 2; ++_i) \
;         __builtin_amdgcn_global_load_lds((const unsigned*)((const char*)(gbase) + (voff)[_i]), (LAS unsigned*)(lds + (bufoff) + ldsw + _i * 8192), 16, 0, 0); } while (0)
; #define PG8_LDA(dst, b, h) do { _Pragma("unroll") for (int m = 0; m < 4; ++m) _Pragma("unroll") for (int k = 0; k < 2; ++k) dst[m][k] = *(const LAS bf16x8*)(lds + PG8_SA(b, h) + aoff + m * 2048 + k * 1024); } while (0)
; #define PG8_MMA(ai, bj, At, Bt) do { __builtin_amdgcn_s_setprio(1); _Pragma("unroll") for (int m = 0; m < 4; ++m) _Pragma("unroll") for (int n = 0; n < 2; ++n) _Pragma("unroll") for (int k = 0; k < 2; ++k) \
;         acc[ai][bj][m][n] = __builtin_amdgcn_mfma_f32_16x16x32_bf16(Bt[n][k], At[m][k], acc[ai][bj][m][n], 0, 0, 0); __builtin_amdgcn_s_setprio(0); } while (0)
; #define PG8_WAIT_V(n) asm volatile("s_waitcnt vmcnt(" #n ")" ::: "memory")
; #define PG8_WAIT_L(n) asm volatile("s_waitcnt lgkmcnt(" #n ")" ::: "memory")
; #define PG8_BAR __builtin_amdgcn_s_barrier()
; #define PG8_SCHED __builtin_amdgcn_sched_barrier(0)
; template <class Epi, class Sched>
; __device__ __forceinline__ void gemm_phase(LAS unsigned char* lds, const int lda, const int ldb, const int K, const Sched& S, const Epi& E, int tid) {
;     ...
;             PG8_LDA(At, 1, 1); PG8_STAGE(PG8_SB(1, 0), b3, voffB); PG8_STAGE(PG8_SB(1, 1), b3 + hB, voffB); PG8_STAGE(PG8_SA(1, 0), a3, voffA);
;             PG8_WAIT_V(8); PG8_WAIT_L(0); PG8_BAR; PG8_MMA(1, 0, At, B0); PG8_MMA(1, 1, At, B1); PG8_BAR; PG8_SCHED;
;         }
	s_add_i32 s8, s34, s18
	s_mov_b32 m0, s8
	ds_read_b128 v[176:179], v159 offset:49152
	ds_read_b128 v[180:183], v159 offset:50176
	ds_read_b128 v[184:187], v159 offset:51200
	ds_read_b128 v[188:191], v159 offset:52224
	ds_read_b128 v[192:195], v159 offset:53248
	ds_read_b128 v[200:203], v159 offset:54272
	ds_read_b128 v[204:207], v159 offset:55296
	ds_read_b128 v[208:211], v159 offset:56320
	global_load_lds_dwordx4 v0, s[98:99]
	s_add_i32 m0, s8, 0x2000
	s_add_u32 s8, s14, 0x18080
	s_addc_u32 s9, s15, 0
	s_add_i32 s14, s35, s18
	global_load_lds_dwordx4 v142, s[98:99]
	s_mov_b32 m0, s14
	s_nop 0
	global_load_lds_dwordx4 v0, s[8:9]
	s_add_i32 m0, s14, 0x2000
	s_nop 0
	global_load_lds_dwordx4 v142, s[8:9]
	s_mov_b32 m0, s23
	s_nop 0
	global_load_lds_dwordx4 v138, s[100:101]
	s_mov_b32 m0, s25
	s_nop 0
	global_load_lds_dwordx4 v140, s[100:101]
	s_waitcnt vmcnt(8)
	s_waitcnt lgkmcnt(0)
	s_barrier
	s_setprio 1
	s_waitcnt lgkmcnt(0)
	v_mfma_f32_16x16x32_bf16 v[94:97], v[130:133], v[176:179], v[94:97]
	v_mfma_f32_16x16x32_bf16 v[90:93], v[148:151], v[176:179], v[90:93]
	v_mfma_f32_16x16x32_bf16 v[86:89], v[130:133], v[184:187], v[86:89]
	v_mfma_f32_16x16x32_bf16 v[82:85], v[148:151], v[184:187], v[82:85]
	v_mfma_f32_16x16x32_bf16 v[78:81], v[130:133], v[192:195], v[78:81]
	v_mfma_f32_16x16x32_bf16 v[70:73], v[148:151], v[192:195], v[70:73]
	v_mfma_f32_16x16x32_bf16 v[62:65], v[130:133], v[204:207], v[62:65]
	v_mfma_f32_16x16x32_bf16 v[58:61], v[148:151], v[204:207], v[58:61]
	v_mfma_f32_16x16x32_bf16 v[94:97], v[134:137], v[180:183], v[94:97]
	v_mfma_f32_16x16x32_bf16 v[90:93], v[152:155], v[180:183], v[90:93]
	v_mfma_f32_16x16x32_bf16 v[86:89], v[134:137], v[188:191], v[86:89]
	v_mfma_f32_16x16x32_bf16 v[82:85], v[152:155], v[188:191], v[82:85]
	v_mfma_f32_16x16x32_bf16 v[78:81], v[134:137], v[200:203], v[78:81]
	v_mfma_f32_16x16x32_bf16 v[70:73], v[152:155], v[200:203], v[70:73]
	v_mfma_f32_16x16x32_bf16 v[62:65], v[134:137], v[208:211], v[62:65]
	v_mfma_f32_16x16x32_bf16 v[58:61], v[152:155], v[208:211], v[58:61]
	s_setprio 0
	s_setprio 1
	v_mfma_f32_16x16x32_bf16 v[30:33], v[160:163], v[176:179], v[30:33]
	v_mfma_f32_16x16x32_bf16 v[26:29], v[168:171], v[176:179], v[26:29]
	v_mfma_f32_16x16x32_bf16 v[22:25], v[160:163], v[184:187], v[22:25]
	v_mfma_f32_16x16x32_bf16 v[18:21], v[168:171], v[184:187], v[18:21]
	v_mfma_f32_16x16x32_bf16 v[14:17], v[160:163], v[192:195], v[14:17]
	v_mfma_f32_16x16x32_bf16 v[10:13], v[168:171], v[192:195], v[10:13]
	v_mfma_f32_16x16x32_bf16 v[6:9], v[160:163], v[204:207], v[6:9]
	v_mfma_f32_16x16x32_bf16 v[2:5], v[168:171], v[204:207], v[2:5]
	v_mfma_f32_16x16x32_bf16 v[30:33], v[164:167], v[180:183], v[30:33]
	v_mfma_f32_16x16x32_bf16 v[26:29], v[172:175], v[180:183], v[26:29]
	v_mfma_f32_16x16x32_bf16 v[22:25], v[164:167], v[188:191], v[22:25]
	v_mfma_f32_16x16x32_bf16 v[18:21], v[172:175], v[188:191], v[18:21]
	v_mfma_f32_16x16x32_bf16 v[14:17], v[164:167], v[200:203], v[14:17]
	v_mfma_f32_16x16x32_bf16 v[10:13], v[172:175], v[200:203], v[10:13]
	v_mfma_f32_16x16x32_bf16 v[6:9], v[164:167], v[208:211], v[6:9]
	v_mfma_f32_16x16x32_bf16 v[2:5], v[172:175], v[208:211], v[2:5]
	s_setprio 0
	s_barrier
	s_add_i32 s44, s44, 2
	s_add_u32 s42, s42, 0x100
	s_addc_u32 s43, s43, 0
	s_cmp_gt_u32 s44, 3
	s_mov_b64 s[8:9], s[10:11]
	s_cbranch_scc0 .LBB0_448
	s_and_b64 vcc, exec, s[2:3]
	s_cbranch_vccz .LBB0_451
	s_barrier

; #define PG8_STAGE(bufoff, gbase, voff) do { _Pragma("unroll") for (int _i = 0; _i < 2; ++_i) \
;         __builtin_amdgcn_global_load_lds((const unsigned*)((const char*)(gbase) + (voff)[_i]), (LAS unsigned*)(lds + (bufoff) + ldsw + _i * 8192), 16, 0, 0); } while (0)
; #define PG8_LDA(dst, b, h) do { _Pragma("unroll") for (int m = 0; m < 4; ++m) _Pragma("unroll") for (int k = 0; k < 2; ++k) dst[m][k] = *(const LAS bf16x8*)(lds + PG8_SA(b, h) + aoff + m * 2048 + k * 1024); } while (0)
; #define PG8_LDB(dst, b, h) do { _Pragma("unroll") for (int n = 0; n < 2; ++n) _Pragma("unroll") for (int k = 0; k < 2; ++k) dst[n][k] = *(const LAS bf16x8*)(lds + PG8_SB(b, h) + boff + n * 2048 + k * 1024); } while (0)
; #define PG8_MMA(ai, bj, At, Bt) do { __builtin_amdgcn_s_setprio(1); _Pragma("unroll") for (int m = 0; m < 4; ++m) _Pragma("unroll") for (int n = 0; n < 2; ++n) _Pragma("unroll") for (int k = 0; k < 2; ++k) \
;         acc[ai][bj][m][n] = __builtin_amdgcn_mfma_f32_16x16x32_bf16(Bt[n][k], At[m][k], acc[ai][bj][m][n], 0, 0, 0); __builtin_amdgcn_s_setprio(0); } while (0)
; template <class Epi, class Sched>
; __device__ __forceinline__ void gemm_phase(LAS unsigned char* lds, const int lda, const int ldb, const int K, const Sched& S, const Epi& E, int tid) {
;     ...
;         for (int t = 0; t < nt; t += 2) {
;             const bool last = (t == nt - 2);
;             const char* a1 = cA + (size_t)(t + 1) * kstep;
;             const char* a2 = last ? nA : cA + (size_t)(t + 2) * kstep; const char* b2 = last ? nB : cB + (size_t)(t + 2) * kstep;
;             const char* a3 = a2 + kstep; const char* b3 = b2 + kstep;
;             PG8_LDB(B0, 0, 0); PG8_LDB(B1, 0, 1); PG8_SCHED; PG8_LDA(At, 0, 0); PG8_STAGE(PG8_SA(1, 1), a1 + hA, voffA);
;             PG8_WAIT_V(8); PG8_WAIT_L(0); PG8_BAR; PG8_MMA(0, 0, At, B0); PG8_MMA(0, 1, At, B1); PG8_BAR; PG8_SCHED;
;             PG8_LDA(At, 0, 1); PG8_STAGE(PG8_SB(0, 0), b2, voffB); PG8_STAGE(PG8_SB(0, 1), b2 + hB, voffB); PG8_STAGE(PG8_SA(0, 0), a2, voffA);
;             PG8_WAIT_V(8); PG8_WAIT_L(0); PG8_BAR; PG8_MMA(1, 0, At, B0); PG8_MMA(1, 1, At, B1); PG8_BAR; PG8_SCHED;
;             PG8_LDB(B0, 1, 0); PG8_LDB(B1, 1, 1); PG8_SCHED; PG8_LDA(At, 1, 0); PG8_STAGE(PG8_SA(0, 1), a2 + hA, voffA);
;             PG8_WAIT_V(8); PG8_WAIT_L(0); PG8_BAR; PG8_MMA(0, 0, At, B0); PG8_MMA(0, 1, At, B1); PG8_BAR; PG8_SCHED;
.LBB0_530:
	s_add_u32 s8, s6, 0xfff80080
	s_addc_u32 s9, s7, -1
	s_add_i32 s16, 0, 0x10000
	s_cmp_eq_u32 s15, 28
	s_cselect_b32 s11, s53, s9
	s_cselect_b32 s10, s52, s8
	v_add_u32_e32 v106, s16, v208
	s_cselect_b32 s9, s55, s14
	s_cselect_b32 s8, s54, s3
	s_add_i32 s22, 0, 0x14000
	ds_read_b128 v[102:105], v106
	ds_read_b128 v[128:131], v106 offset:1024
	ds_read_b128 v[132:135], v106 offset:2048
	ds_read_b128 v[154:157], v106 offset:3072
	v_add_u32_e32 v106, s22, v208
	ds_read_b128 v[158:161], v106
	ds_read_b128 v[162:165], v106 offset:1024
	ds_read_b128 v[166:169], v106 offset:2048
	ds_read_b128 v[170:173], v106 offset:3072
	s_add_i32 m0, s20, 0xc000
	ds_read_b128 v[174:177], v210
	ds_read_b128 v[178:181], v210 offset:1024
	ds_read_b128 v[182:185], v210 offset:2048
	ds_read_b128 v[186:189], v210 offset:3072
	ds_read_b128 v[190:193], v210 offset:4096
	ds_read_b128 v[194:197], v210 offset:5120
	ds_read_b128 v[200:203], v210 offset:6144
	ds_read_b128 v[204:207], v210 offset:7168
	global_load_lds_dwordx4 v150, s[6:7]
	s_add_i32 m0, s20, 0xe000
	s_nop 0
	global_load_lds_dwordx4 v152, s[6:7]
	s_waitcnt vmcnt(8)
	s_waitcnt lgkmcnt(0)
	s_barrier
	s_setprio 1
	s_waitcnt lgkmcnt(0)
	v_mfma_f32_16x16x32_bf16 v[140:143], v[102:105], v[174:177], v[140:143]
	v_mfma_f32_16x16x32_bf16 v[94:97], v[132:135], v[174:177], v[94:97]
	v_mfma_f32_16x16x32_bf16 v[136:139], v[102:105], v[182:185], v[136:139]
	v_mfma_f32_16x16x32_bf16 v[90:93], v[132:135], v[182:185], v[90:93]
	v_mfma_f32_16x16x32_bf16 v[124:127], v[102:105], v[190:193], v[124:127]
	v_mfma_f32_16x16x32_bf16 v[86:89], v[132:135], v[190:193], v[86:89]
	v_mfma_f32_16x16x32_bf16 v[120:123], v[102:105], v[200:203], v[120:123]
	v_mfma_f32_16x16x32_bf16 v[82:85], v[132:135], v[200:203], v[82:85]
	v_mfma_f32_16x16x32_bf16 v[140:143], v[128:131], v[178:181], v[140:143]
	v_mfma_f32_16x16x32_bf16 v[94:97], v[154:157], v[178:181], v[94:97]
	v_mfma_f32_16x16x32_bf16 v[136:139], v[128:131], v[186:189], v[136:139]
	v_mfma_f32_16x16x32_bf16 v[90:93], v[154:157], v[186:189], v[90:93]
	v_mfma_f32_16x16x32_bf16 v[124:127], v[128:131], v[194:197], v[124:127]
	v_mfma_f32_16x16x32_bf16 v[86:89], v[154:157], v[194:197], v[86:89]
	v_mfma_f32_16x16x32_bf16 v[120:123], v[128:131], v[204:207], v[120:123]
	v_mfma_f32_16x16x32_bf16 v[82:85], v[154:157], v[204:207], v[82:85]
	s_setprio 0
	s_setprio 1
	v_mfma_f32_16x16x32_bf16 v[62:65], v[158:161], v[174:177], v[62:65]
	v_mfma_f32_16x16x32_bf16 v[34:37], v[166:169], v[174:177], v[34:37]
	v_mfma_f32_16x16x32_bf16 v[58:61], v[158:161], v[182:185], v[58:61]
	v_mfma_f32_16x16x32_bf16 v[26:29], v[166:169], v[182:185], v[26:29]
	v_mfma_f32_16x16x32_bf16 v[54:57], v[158:161], v[190:193], v[54:57]
	v_mfma_f32_16x16x32_bf16 v[22:25], v[166:169], v[190:193], v[22:25]
	v_mfma_f32_16x16x32_bf16 v[50:53], v[158:161], v[200:203], v[50:53]
	v_mfma_f32_16x16x32_bf16 v[18:21], v[166:169], v[200:203], v[18:21]
	v_mfma_f32_16x16x32_bf16 v[62:65], v[162:165], v[178:181], v[62:65]
	v_mfma_f32_16x16x32_bf16 v[34:37], v[170:173], v[178:181], v[34:37]
	v_mfma_f32_16x16x32_bf16 v[58:61], v[162:165], v[186:189], v[58:61]
	v_mfma_f32_16x16x32_bf16 v[26:29], v[170:173], v[186:189], v[26:29]
	v_mfma_f32_16x16x32_bf16 v[54:57], v[162:165], v[194:197], v[54:57]
	v_mfma_f32_16x16x32_bf16 v[22:25], v[170:173], v[194:197], v[22:25]
	v_mfma_f32_16x16x32_bf16 v[50:53], v[162:165], v[204:207], v[50:53]
	v_mfma_f32_16x16x32_bf16 v[18:21], v[170:173], v[204:207], v[18:21]
	s_setprio 0
	s_barrier
	s_add_u32 s98, s8, s30
	s_addc_u32 s99, s9, s31
	s_add_u32 s100, s10, s30
	s_addc_u32 s101, s11, s31
	s_add_i32 s16, s16, s5
	s_mov_b32 m0, s16
	ds_read_b128 v[174:177], v210 offset:16384
	ds_read_b128 v[178:181], v210 offset:17408
	ds_read_b128 v[182:185], v210 offset:18432
	ds_read_b128 v[186:189], v210 offset:19456
	ds_read_b128 v[190:193], v210 offset:20480
	ds_read_b128 v[194:197], v210 offset:21504
	ds_read_b128 v[200:203], v210 offset:22528
	ds_read_b128 v[204:207], v210 offset:23552
	global_load_lds_dwordx4 v0, s[8:9]
	s_add_i32 m0, s16, 0x2000
	s_add_u32 s16, s8, 0x80000
	s_addc_u32 s17, s9, 0
	s_add_i32 s22, s22, s5
	global_load_lds_dwordx4 v148, s[8:9]
	s_mov_b32 m0, s22
	s_nop 0
	global_load_lds_dwordx4 v0, s[16:17]
	s_add_i32 m0, s22, 0x2000
	s_nop 0
	global_load_lds_dwordx4 v148, s[16:17]
	s_mov_b32 m0, s20
	s_nop 0
	global_load_lds_dwordx4 v144, s[10:11]
	s_mov_b32 m0, s21
	s_nop 0
	global_load_lds_dwordx4 v146, s[10:11]
	s_waitcnt vmcnt(8)
	s_waitcnt lgkmcnt(0)
	s_barrier
	s_setprio 1
	s_waitcnt lgkmcnt(0)
	v_mfma_f32_16x16x32_bf16 v[116:119], v[102:105], v[174:177], v[116:119]
	v_mfma_f32_16x16x32_bf16 v[78:81], v[132:135], v[174:177], v[78:81]
	v_mfma_f32_16x16x32_bf16 v[112:115], v[102:105], v[182:185], v[112:115]
	v_mfma_f32_16x16x32_bf16 v[74:77], v[132:135], v[182:185], v[74:77]
	v_mfma_f32_16x16x32_bf16 v[106:109], v[102:105], v[190:193], v[108:111]
	v_mfma_f32_16x16x32_bf16 v[70:73], v[132:135], v[190:193], v[70:73]
	v_mfma_f32_16x16x32_bf16 v[98:101], v[102:105], v[200:203], v[98:101]
	v_mfma_f32_16x16x32_bf16 v[66:69], v[132:135], v[200:203], v[66:69]
	v_mfma_f32_16x16x32_bf16 v[116:119], v[128:131], v[178:181], v[116:119]
	v_mfma_f32_16x16x32_bf16 v[78:81], v[154:157], v[178:181], v[78:81]
	v_mfma_f32_16x16x32_bf16 v[112:115], v[128:131], v[186:189], v[112:115]
	v_mfma_f32_16x16x32_bf16 v[74:77], v[154:157], v[186:189], v[74:77]
	v_mfma_f32_16x16x32_bf16 v[106:109], v[128:131], v[194:197], v[106:109]
	v_mfma_f32_16x16x32_bf16 v[70:73], v[154:157], v[194:197], v[70:73]
	v_mfma_f32_16x16x32_bf16 v[98:101], v[128:131], v[204:207], v[98:101]
	v_mfma_f32_16x16x32_bf16 v[66:69], v[154:157], v[204:207], v[66:69]
	s_setprio 0
	s_setprio 1
	v_mfma_f32_16x16x32_bf16 v[46:49], v[158:161], v[174:177], v[46:49]
	v_mfma_f32_16x16x32_bf16 v[14:17], v[166:169], v[174:177], v[14:17]
	v_mfma_f32_16x16x32_bf16 v[42:45], v[158:161], v[182:185], v[42:45]
	v_mfma_f32_16x16x32_bf16 v[10:13], v[166:169], v[182:185], v[10:13]
	v_mfma_f32_16x16x32_bf16 v[38:41], v[158:161], v[190:193], v[38:41]
	v_mfma_f32_16x16x32_bf16 v[6:9], v[166:169], v[190:193], v[6:9]
	v_mfma_f32_16x16x32_bf16 v[30:33], v[158:161], v[200:203], v[30:33]
	v_mfma_f32_16x16x32_bf16 v[2:5], v[166:169], v[200:203], v[2:5]
	v_mfma_f32_16x16x32_bf16 v[46:49], v[162:165], v[178:181], v[46:49]
	v_mfma_f32_16x16x32_bf16 v[14:17], v[170:173], v[178:181], v[14:17]
	v_mfma_f32_16x16x32_bf16 v[42:45], v[162:165], v[186:189], v[42:45]
	v_mfma_f32_16x16x32_bf16 v[10:13], v[170:173], v[186:189], v[10:13]
	v_mfma_f32_16x16x32_bf16 v[38:41], v[162:165], v[194:197], v[38:41]
	v_mfma_f32_16x16x32_bf16 v[6:9], v[170:173], v[194:197], v[6:9]
	v_mfma_f32_16x16x32_bf16 v[30:33], v[162:165], v[204:207], v[30:33]
	v_mfma_f32_16x16x32_bf16 v[2:5], v[170:173], v[204:207], v[2:5]
	s_setprio 0
	s_barrier
; #define PG8_STAGE(bufoff, gbase, voff) do { _Pragma("unroll") for (int _i = 0; _i < 2; ++_i) \
;         __builtin_amdgcn_global_load_lds((const unsigned*)((const char*)(gbase) + (voff)[_i]), (LAS unsigned*)(lds + (bufoff) + ldsw + _i * 8192), 16, 0, 0); } while (0)
; #define PG8_LDA(dst, b, h) do { _Pragma("unroll") for (int m = 0; m < 4; ++m) _Pragma("unroll") for (int k = 0; k < 2; ++k) dst[m][k] = *(const LAS bf16x8*)(lds + PG8_SA(b, h) + aoff + m * 2048 + k * 1024); } while (0)
; #define PG8_LDB(dst, b, h) do { _Pragma("unroll") for (int n = 0; n < 2; ++n) _Pragma("unroll") for (int k = 0; k < 2; ++k) dst[n][k] = *(const LAS bf16x8*)(lds + PG8_SB(b, h) + boff + n * 2048 + k * 1024); } while (0)
; #define PG8_MMA(ai, bj, At, Bt) do { __builtin_amdgcn_s_setprio(1); _Pragma("unroll") for (int m = 0; m < 4; ++m) _Pragma("unroll") for (int n = 0; n < 2; ++n) _Pragma("unroll") for (int k = 0; k < 2; ++k) \
;         acc[ai][bj][m][n] = __builtin_amdgcn_mfma_f32_16x16x32_bf16(Bt[n][k], At[m][k], acc[ai][bj][m][n], 0, 0, 0); __builtin_amdgcn_s_setprio(0); } while (0)
; #define PG8_WAIT_V(n) asm volatile("s_waitcnt vmcnt(" #n ")" ::: "memory")
; #define PG8_WAIT_L(n) asm volatile("s_waitcnt lgkmcnt(" #n ")" ::: "memory")
; #define PG8_BAR __builtin_amdgcn_s_barrier()
; #define PG8_SCHED __builtin_amdgcn_sched_barrier(0)
; template <class Epi, class Sched>
; __device__ __forceinline__ void gemm_phase(LAS unsigned char* lds, const int lda, const int ldb, const int K, const Sched& S, const Epi& E, int tid) {
;     ...
;             PG8_LDB(B0, 1, 0); PG8_LDB(B1, 1, 1); PG8_SCHED; PG8_LDA(At, 1, 0); PG8_STAGE(PG8_SA(0, 1), a2 + hA, voffA);
;             PG8_WAIT_V(8); PG8_WAIT_L(0); PG8_BAR; PG8_MMA(0, 0, At, B0); PG8_MMA(0, 1, At, B1); PG8_BAR; PG8_SCHED;
;             PG8_LDA(At, 1, 1); PG8_STAGE(PG8_SB(1, 0), b3, voffB); PG8_STAGE(PG8_SB(1, 1), b3 + hB, voffB); PG8_STAGE(PG8_SA(1, 0), a3, voffA);
;             PG8_WAIT_V(8); PG8_WAIT_L(0); PG8_BAR; PG8_MMA(1, 0, At, B0); PG8_MMA(1, 1, At, B1); PG8_BAR; PG8_SCHED;
;         }
	s_add_i32 s16, 0, 0x18000
	v_add_u32_e32 v110, s16, v208
	s_add_i32 s17, 0, 0x1c000
	ds_read_b128 v[102:105], v110
	ds_read_b128 v[128:131], v110 offset:1024
	ds_read_b128 v[132:135], v110 offset:2048
	ds_read_b128 v[154:157], v110 offset:3072
	v_add_u32_e32 v110, s17, v208
	ds_read_b128 v[158:161], v110
	ds_read_b128 v[162:165], v110 offset:1024
	ds_read_b128 v[166:169], v110 offset:2048
	ds_read_b128 v[170:173], v110 offset:3072
	s_add_u32 s10, s10, 0x80000
	s_addc_u32 s11, s11, 0
	s_mov_b32 m0, s26
	ds_read_b128 v[174:177], v210 offset:32768
	ds_read_b128 v[178:181], v210 offset:33792
	ds_read_b128 v[182:185], v210 offset:34816
	ds_read_b128 v[186:189], v210 offset:35840
	ds_read_b128 v[190:193], v210 offset:36864
	ds_read_b128 v[194:197], v210 offset:37888
	ds_read_b128 v[200:203], v210 offset:38912
	ds_read_b128 v[204:207], v210 offset:39936
	global_load_lds_dwordx4 v144, s[10:11]
	s_mov_b32 m0, s27
	s_nop 0
	global_load_lds_dwordx4 v146, s[10:11]
	s_waitcnt vmcnt(8)
	s_waitcnt lgkmcnt(0)
	s_barrier
	s_setprio 1
	s_waitcnt lgkmcnt(0)
	v_mfma_f32_16x16x32_bf16 v[140:143], v[102:105], v[174:177], v[140:143]
	v_mfma_f32_16x16x32_bf16 v[94:97], v[132:135], v[174:177], v[94:97]
	v_mfma_f32_16x16x32_bf16 v[136:139], v[102:105], v[182:185], v[136:139]
	v_mfma_f32_16x16x32_bf16 v[90:93], v[132:135], v[182:185], v[90:93]
	v_mfma_f32_16x16x32_bf16 v[124:127], v[102:105], v[190:193], v[124:127]
	v_mfma_f32_16x16x32_bf16 v[86:89], v[132:135], v[190:193], v[86:89]
	v_mfma_f32_16x16x32_bf16 v[120:123], v[102:105], v[200:203], v[120:123]
	v_mfma_f32_16x16x32_bf16 v[82:85], v[132:135], v[200:203], v[82:85]
	v_mfma_f32_16x16x32_bf16 v[140:143], v[128:131], v[178:181], v[140:143]
	v_mfma_f32_16x16x32_bf16 v[94:97], v[154:157], v[178:181], v[94:97]
	v_mfma_f32_16x16x32_bf16 v[136:139], v[128:131], v[186:189], v[136:139]
	v_mfma_f32_16x16x32_bf16 v[90:93], v[154:157], v[186:189], v[90:93]
	v_mfma_f32_16x16x32_bf16 v[124:127], v[128:131], v[194:197], v[124:127]
	v_mfma_f32_16x16x32_bf16 v[86:89], v[154:157], v[194:197], v[86:89]
	v_mfma_f32_16x16x32_bf16 v[120:123], v[128:131], v[204:207], v[120:123]
	v_mfma_f32_16x16x32_bf16 v[82:85], v[154:157], v[204:207], v[82:85]
	s_setprio 0
	s_setprio 1
	v_mfma_f32_16x16x32_bf16 v[62:65], v[158:161], v[174:177], v[62:65]
	v_mfma_f32_16x16x32_bf16 v[34:37], v[166:169], v[174:177], v[34:37]
	v_mfma_f32_16x16x32_bf16 v[58:61], v[158:161], v[182:185], v[58:61]
	v_mfma_f32_16x16x32_bf16 v[26:29], v[166:169], v[182:185], v[26:29]
	v_mfma_f32_16x16x32_bf16 v[54:57], v[158:161], v[190:193], v[54:57]
	v_mfma_f32_16x16x32_bf16 v[22:25], v[166:169], v[190:193], v[22:25]
	v_mfma_f32_16x16x32_bf16 v[50:53], v[158:161], v[200:203], v[50:53]
	v_mfma_f32_16x16x32_bf16 v[18:21], v[166:169], v[200:203], v[18:21]
	v_mfma_f32_16x16x32_bf16 v[62:65], v[162:165], v[178:181], v[62:65]
	v_mfma_f32_16x16x32_bf16 v[34:37], v[170:173], v[178:181], v[34:37]
	v_mfma_f32_16x16x32_bf16 v[58:61], v[162:165], v[186:189], v[58:61]
	v_mfma_f32_16x16x32_bf16 v[26:29], v[170:173], v[186:189], v[26:29]
	v_mfma_f32_16x16x32_bf16 v[54:57], v[162:165], v[194:197], v[54:57]
	v_mfma_f32_16x16x32_bf16 v[22:25], v[170:173], v[194:197], v[22:25]
	v_mfma_f32_16x16x32_bf16 v[50:53], v[162:165], v[204:207], v[50:53]
	v_mfma_f32_16x16x32_bf16 v[18:21], v[170:173], v[204:207], v[18:21]
	s_setprio 0
	s_barrier
	s_add_i32 s10, s16, s5
	s_mov_b32 m0, s10
	ds_read_b128 v[174:177], v210 offset:49152
	ds_read_b128 v[178:181], v210 offset:50176
	ds_read_b128 v[182:185], v210 offset:51200
	ds_read_b128 v[186:189], v210 offset:52224
	ds_read_b128 v[190:193], v210 offset:53248
	ds_read_b128 v[194:197], v210 offset:54272
	ds_read_b128 v[200:203], v210 offset:55296
	ds_read_b128 v[204:207], v210 offset:56320
	global_load_lds_dwordx4 v0, s[98:99]
	s_add_i32 m0, s10, 0x2000
	s_add_u32 s8, s8, 0x80080
	s_addc_u32 s9, s9, 0
	s_add_i32 s10, s17, s5
	global_load_lds_dwordx4 v148, s[98:99]
	s_mov_b32 m0, s10
	s_nop 0
	global_load_lds_dwordx4 v0, s[8:9]
	s_add_i32 m0, s10, 0x2000
	s_nop 0
	global_load_lds_dwordx4 v148, s[8:9]
	s_mov_b32 m0, s25
	s_nop 0
	global_load_lds_dwordx4 v144, s[100:101]
	s_mov_b32 m0, s56
	s_nop 0
	global_load_lds_dwordx4 v146, s[100:101]
	s_waitcnt vmcnt(8)
	s_waitcnt lgkmcnt(0)
	s_barrier
	s_setprio 1
	s_waitcnt lgkmcnt(0)
	v_mfma_f32_16x16x32_bf16 v[116:119], v[102:105], v[174:177], v[116:119]
	v_mfma_f32_16x16x32_bf16 v[78:81], v[132:135], v[174:177], v[78:81]
	v_mfma_f32_16x16x32_bf16 v[110:113], v[102:105], v[182:185], v[112:115]
	v_mfma_f32_16x16x32_bf16 v[74:77], v[132:135], v[182:185], v[74:77]
	v_mfma_f32_16x16x32_bf16 v[106:109], v[102:105], v[190:193], v[106:109]
	v_mfma_f32_16x16x32_bf16 v[70:73], v[132:135], v[190:193], v[70:73]
	v_mfma_f32_16x16x32_bf16 v[98:101], v[102:105], v[200:203], v[98:101]
	v_mfma_f32_16x16x32_bf16 v[66:69], v[132:135], v[200:203], v[66:69]
	v_mfma_f32_16x16x32_bf16 v[116:119], v[128:131], v[178:181], v[116:119]
	v_mfma_f32_16x16x32_bf16 v[78:81], v[154:157], v[178:181], v[78:81]
	v_mfma_f32_16x16x32_bf16 v[112:115], v[128:131], v[186:189], v[110:113]
	v_mfma_f32_16x16x32_bf16 v[74:77], v[154:157], v[186:189], v[74:77]
	v_mfma_f32_16x16x32_bf16 v[108:111], v[128:131], v[194:197], v[106:109]
	v_mfma_f32_16x16x32_bf16 v[70:73], v[154:157], v[194:197], v[70:73]
	v_mfma_f32_16x16x32_bf16 v[98:101], v[128:131], v[204:207], v[98:101]
	v_mfma_f32_16x16x32_bf16 v[66:69], v[154:157], v[204:207], v[66:69]
	s_setprio 0
	s_setprio 1
	v_mfma_f32_16x16x32_bf16 v[46:49], v[158:161], v[174:177], v[46:49]
	v_mfma_f32_16x16x32_bf16 v[14:17], v[166:169], v[174:177], v[14:17]
	v_mfma_f32_16x16x32_bf16 v[42:45], v[158:161], v[182:185], v[42:45]
	v_mfma_f32_16x16x32_bf16 v[10:13], v[166:169], v[182:185], v[10:13]
	v_mfma_f32_16x16x32_bf16 v[38:41], v[158:161], v[190:193], v[38:41]
	v_mfma_f32_16x16x32_bf16 v[6:9], v[166:169], v[190:193], v[6:9]
	v_mfma_f32_16x16x32_bf16 v[30:33], v[158:161], v[200:203], v[30:33]
	v_mfma_f32_16x16x32_bf16 v[2:5], v[166:169], v[200:203], v[2:5]
	v_mfma_f32_16x16x32_bf16 v[46:49], v[162:165], v[178:181], v[46:49]
	v_mfma_f32_16x16x32_bf16 v[14:17], v[170:173], v[178:181], v[14:17]
	v_mfma_f32_16x16x32_bf16 v[42:45], v[162:165], v[186:189], v[42:45]
	v_mfma_f32_16x16x32_bf16 v[10:13], v[170:173], v[186:189], v[10:13]
	v_mfma_f32_16x16x32_bf16 v[38:41], v[162:165], v[194:197], v[38:41]
	v_mfma_f32_16x16x32_bf16 v[6:9], v[170:173], v[194:197], v[6:9]
	v_mfma_f32_16x16x32_bf16 v[30:33], v[162:165], v[204:207], v[30:33]
	v_mfma_f32_16x16x32_bf16 v[2:5], v[170:173], v[204:207], v[2:5]
	s_setprio 0
	s_barrier
	s_add_i32 s15, s15, 2
	s_add_u32 s6, s6, 0x100
	s_addc_u32 s7, s7, 0
	s_add_u32 s3, s3, 0x100
	s_addc_u32 s14, s14, 0
	s_cmp_gt_u32 s15, 29
	s_cbranch_scc0 .LBB0_530
	s_and_b64 vcc, exec, s[48:49]
	s_cbranch_vccz .LBB0_533
	s_barrier

; #define PG8_STAGE(bufoff, gbase, voff) do { _Pragma("unroll") for (int _i = 0; _i < 2; ++_i) \
;         __builtin_amdgcn_global_load_lds((const unsigned*)((const char*)(gbase) + (voff)[_i]), (LAS unsigned*)(lds + (bufoff) + ldsw + _i * 8192), 16, 0, 0); } while (0)
; #define PG8_LDA(dst, b, h) do { _Pragma("unroll") for (int m = 0; m < 4; ++m) _Pragma("unroll") for (int k = 0; k < 2; ++k) dst[m][k] = *(const LAS bf16x8*)(lds + PG8_SA(b, h) + aoff + m * 2048 + k * 1024); } while (0)
; #define PG8_LDB(dst, b, h) do { _Pragma("unroll") for (int n = 0; n < 2; ++n) _Pragma("unroll") for (int k = 0; k < 2; ++k) dst[n][k] = *(const LAS bf16x8*)(lds + PG8_SB(b, h) + boff + n * 2048 + k * 1024); } while (0)
; #define PG8_MMA(ai, bj, At, Bt) do { __builtin_amdgcn_s_setprio(1); _Pragma("unroll") for (int m = 0; m < 4; ++m) _Pragma("unroll") for (int n = 0; n < 2; ++n) _Pragma("unroll") for (int k = 0; k < 2; ++k) \
;         acc[ai][bj][m][n] = __builtin_amdgcn_mfma_f32_16x16x32_bf16(Bt[n][k], At[m][k], acc[ai][bj][m][n], 0, 0, 0); __builtin_amdgcn_s_setprio(0); } while (0)
; #define PG8_WAIT_V(n) asm volatile("s_waitcnt vmcnt(" #n ")" ::: "memory")
; #define PG8_WAIT_L(n) asm volatile("s_waitcnt lgkmcnt(" #n ")" ::: "memory")
; #define PG8_BAR __builtin_amdgcn_s_barrier()
; #define PG8_SCHED __builtin_amdgcn_sched_barrier(0)
; template <class Epi, class Sched>
; __device__ __forceinline__ void gemm_phase(LAS unsigned char* lds, const int lda, const int ldb, const int K, const Sched& S, const Epi& E, int tid) {
;     ...
;             const bool last = (t == nt - 2);
;             const char* a1 = cA + (size_t)(t + 1) * kstep;
;             const char* a2 = last ? nA : cA + (size_t)(t + 2) * kstep; const char* b2 = last ? nB : cB + (size_t)(t + 2) * kstep;
;             const char* a3 = a2 + kstep; const char* b3 = b2 + kstep;
;             PG8_LDB(B0, 0, 0); PG8_LDB(B1, 0, 1); PG8_SCHED; PG8_LDA(At, 0, 0); PG8_STAGE(PG8_SA(1, 1), a1 + hA, voffA);
;             PG8_WAIT_V(8); PG8_WAIT_L(0); PG8_BAR; PG8_MMA(0, 0, At, B0); PG8_MMA(0, 1, At, B1); PG8_BAR; PG8_SCHED;
;             PG8_LDA(At, 0, 1); PG8_STAGE(PG8_SB(0, 0), b2, voffB); PG8_STAGE(PG8_SB(0, 1), b2 + hB, voffB); PG8_STAGE(PG8_SA(0, 0), a2, voffA);
;             PG8_WAIT_V(8); PG8_WAIT_L(0); PG8_BAR; PG8_MMA(1, 0, At, B0); PG8_MMA(1, 1, At, B1); PG8_BAR; PG8_SCHED;
.LBB0_880:
	s_add_u32 s4, s2, 0x100
	s_addc_u32 s5, s3, 0
	s_add_i32 s33, 0, 0x10000
	s_cmpk_eq_i32 s29, 0x54
	s_cselect_b32 s9, s49, s5
	s_cselect_b32 s8, s48, s4
	s_cselect_b32 s7, s51, s28
	s_cselect_b32 s6, s50, s25
	s_add_i32 s34, 0, 0x14000
	v_add_u32_e32 v130, s33, v208
	v_add_u32_e32 v168, s34, v208
	ds_read_b128 v[82:85], v130
	ds_read_b128 v[86:89], v130 offset:1024
	ds_read_b128 v[126:129], v130 offset:2048
	ds_read_b128 v[130:133], v130 offset:3072
	ds_read_b128 v[156:159], v168
	ds_read_b128 v[160:163], v168 offset:1024
	ds_read_b128 v[164:167], v168 offset:2048
	ds_read_b128 v[168:171], v168 offset:3072
	s_add_i32 m0, s15, 0xc000
	ds_read_b128 v[172:175], v210
	ds_read_b128 v[176:179], v210 offset:1024
	ds_read_b128 v[180:183], v210 offset:2048
	ds_read_b128 v[184:187], v210 offset:3072
	ds_read_b128 v[188:191], v210 offset:4096
	ds_read_b128 v[192:195], v210 offset:5120
	ds_read_b128 v[200:203], v210 offset:6144
	ds_read_b128 v[204:207], v210 offset:7168
	global_load_lds_dwordx4 v152, s[2:3]
	s_add_i32 m0, s15, 0xe000
	s_nop 0
	global_load_lds_dwordx4 v154, s[2:3]
	s_waitcnt vmcnt(8)
	s_waitcnt lgkmcnt(0)
	s_barrier
	s_setprio 1
	s_waitcnt lgkmcnt(0)
	v_mfma_f32_16x16x32_bf16 v[142:145], v[82:85], v[172:175], v[142:145]
	v_mfma_f32_16x16x32_bf16 v[102:105], v[126:129], v[172:175], v[102:105]
	v_mfma_f32_16x16x32_bf16 v[138:141], v[82:85], v[180:183], v[138:141]
	v_mfma_f32_16x16x32_bf16 v[98:101], v[126:129], v[180:183], v[98:101]
	v_mfma_f32_16x16x32_bf16 v[134:137], v[82:85], v[188:191], v[134:137]
	v_mfma_f32_16x16x32_bf16 v[94:97], v[126:129], v[188:191], v[94:97]
	v_mfma_f32_16x16x32_bf16 v[122:125], v[82:85], v[200:203], v[122:125]
	v_mfma_f32_16x16x32_bf16 v[90:93], v[126:129], v[200:203], v[90:93]
	v_mfma_f32_16x16x32_bf16 v[142:145], v[86:89], v[176:179], v[142:145]
	v_mfma_f32_16x16x32_bf16 v[102:105], v[130:133], v[176:179], v[102:105]
	v_mfma_f32_16x16x32_bf16 v[138:141], v[86:89], v[184:187], v[138:141]
	v_mfma_f32_16x16x32_bf16 v[98:101], v[130:133], v[184:187], v[98:101]
	v_mfma_f32_16x16x32_bf16 v[134:137], v[86:89], v[192:195], v[134:137]
	v_mfma_f32_16x16x32_bf16 v[94:97], v[130:133], v[192:195], v[94:97]
	v_mfma_f32_16x16x32_bf16 v[122:125], v[86:89], v[204:207], v[122:125]
	v_mfma_f32_16x16x32_bf16 v[90:93], v[130:133], v[204:207], v[90:93]
	s_setprio 0
	s_setprio 1
	v_mfma_f32_16x16x32_bf16 v[66:69], v[156:159], v[172:175], v[66:69]
	v_mfma_f32_16x16x32_bf16 v[34:37], v[164:167], v[172:175], v[34:37]
	v_mfma_f32_16x16x32_bf16 v[58:61], v[156:159], v[180:183], v[58:61]
	v_mfma_f32_16x16x32_bf16 v[26:29], v[164:167], v[180:183], v[26:29]
	v_mfma_f32_16x16x32_bf16 v[54:57], v[156:159], v[188:191], v[54:57]
	v_mfma_f32_16x16x32_bf16 v[22:25], v[164:167], v[188:191], v[22:25]
	v_mfma_f32_16x16x32_bf16 v[50:53], v[156:159], v[200:203], v[50:53]
	v_mfma_f32_16x16x32_bf16 v[18:21], v[164:167], v[200:203], v[18:21]
	v_mfma_f32_16x16x32_bf16 v[66:69], v[160:163], v[176:179], v[66:69]
	v_mfma_f32_16x16x32_bf16 v[34:37], v[168:171], v[176:179], v[34:37]
	v_mfma_f32_16x16x32_bf16 v[58:61], v[160:163], v[184:187], v[58:61]
	v_mfma_f32_16x16x32_bf16 v[26:29], v[168:171], v[184:187], v[26:29]
	v_mfma_f32_16x16x32_bf16 v[54:57], v[160:163], v[192:195], v[54:57]
	v_mfma_f32_16x16x32_bf16 v[22:25], v[168:171], v[192:195], v[22:25]
	v_mfma_f32_16x16x32_bf16 v[50:53], v[160:163], v[204:207], v[50:53]
	v_mfma_f32_16x16x32_bf16 v[18:21], v[168:171], v[204:207], v[18:21]
	s_setprio 0
	s_barrier
	s_add_u32 s98, s6, s30
	s_addc_u32 s99, s7, s31
	s_add_u32 s100, s8, s30
	s_addc_u32 s101, s9, s31
	s_add_i32 s2, s33, s14
	s_mov_b32 m0, s2
	ds_read_b128 v[172:175], v210 offset:16384
	ds_read_b128 v[176:179], v210 offset:17408
	ds_read_b128 v[180:183], v210 offset:18432
	ds_read_b128 v[184:187], v210 offset:19456
	ds_read_b128 v[188:191], v210 offset:20480
	ds_read_b128 v[192:195], v210 offset:21504
	ds_read_b128 v[200:203], v210 offset:22528
	ds_read_b128 v[204:207], v210 offset:23552
	global_load_lds_dwordx4 v0, s[6:7]
	s_add_i32 m0, s2, 0x2000
	s_add_u32 s2, s6, 0x160000
	s_addc_u32 s3, s7, 0
	s_add_i32 s33, s34, s14
	global_load_lds_dwordx4 v150, s[6:7]
	s_mov_b32 m0, s33
	s_nop 0
	global_load_lds_dwordx4 v0, s[2:3]
	s_add_i32 m0, s33, 0x2000
	s_nop 0
	global_load_lds_dwordx4 v150, s[2:3]
	s_mov_b32 m0, s15
	s_nop 0
	global_load_lds_dwordx4 v146, s[8:9]
	s_mov_b32 m0, s16
	s_nop 0
	global_load_lds_dwordx4 v148, s[8:9]
	s_waitcnt vmcnt(8)
	s_waitcnt lgkmcnt(0)
	s_barrier
	s_setprio 1
	s_waitcnt lgkmcnt(0)
	v_mfma_f32_16x16x32_bf16 v[118:121], v[82:85], v[172:175], v[118:121]
	v_mfma_f32_16x16x32_bf16 v[78:81], v[126:129], v[172:175], v[78:81]
	v_mfma_f32_16x16x32_bf16 v[114:117], v[82:85], v[180:183], v[114:117]
	v_mfma_f32_16x16x32_bf16 v[74:77], v[126:129], v[180:183], v[74:77]
	v_mfma_f32_16x16x32_bf16 v[110:113], v[82:85], v[188:191], v[110:113]
	v_mfma_f32_16x16x32_bf16 v[70:73], v[126:129], v[188:191], v[70:73]
	v_mfma_f32_16x16x32_bf16 v[62:65], v[126:129], v[200:203], v[62:65]
	v_mfma_f32_16x16x32_bf16 v[118:121], v[86:89], v[176:179], v[118:121]
	v_mfma_f32_16x16x32_bf16 v[78:81], v[130:133], v[176:179], v[78:81]
	v_mfma_f32_16x16x32_bf16 v[114:117], v[86:89], v[184:187], v[114:117]
	v_mfma_f32_16x16x32_bf16 v[74:77], v[130:133], v[184:187], v[74:77]
	v_mfma_f32_16x16x32_bf16 v[110:113], v[86:89], v[192:195], v[110:113]
	v_mfma_f32_16x16x32_bf16 v[70:73], v[130:133], v[192:195], v[70:73]
	v_mfma_f32_16x16x32_bf16 v[82:85], v[82:85], v[200:203], v[106:109]
	v_mfma_f32_16x16x32_bf16 v[62:65], v[130:133], v[204:207], v[62:65]
	v_mfma_f32_16x16x32_bf16 v[82:85], v[86:89], v[204:207], v[82:85]
	s_setprio 0
	s_setprio 1
	v_mfma_f32_16x16x32_bf16 v[46:49], v[156:159], v[172:175], v[46:49]
	v_mfma_f32_16x16x32_bf16 v[14:17], v[164:167], v[172:175], v[14:17]
	v_mfma_f32_16x16x32_bf16 v[42:45], v[156:159], v[180:183], v[42:45]
	v_mfma_f32_16x16x32_bf16 v[10:13], v[164:167], v[180:183], v[10:13]
	v_mfma_f32_16x16x32_bf16 v[38:41], v[156:159], v[188:191], v[38:41]
	v_mfma_f32_16x16x32_bf16 v[6:9], v[164:167], v[188:191], v[6:9]
	v_mfma_f32_16x16x32_bf16 v[30:33], v[156:159], v[200:203], v[30:33]
	v_mfma_f32_16x16x32_bf16 v[2:5], v[164:167], v[200:203], v[2:5]
	v_mfma_f32_16x16x32_bf16 v[46:49], v[160:163], v[176:179], v[46:49]
	v_mfma_f32_16x16x32_bf16 v[14:17], v[168:171], v[176:179], v[14:17]
	v_mfma_f32_16x16x32_bf16 v[42:45], v[160:163], v[184:187], v[42:45]
	v_mfma_f32_16x16x32_bf16 v[10:13], v[168:171], v[184:187], v[10:13]
	v_mfma_f32_16x16x32_bf16 v[38:41], v[160:163], v[192:195], v[38:41]
	v_mfma_f32_16x16x32_bf16 v[6:9], v[168:171], v[192:195], v[6:9]
	v_mfma_f32_16x16x32_bf16 v[30:33], v[160:163], v[204:207], v[30:33]
	v_mfma_f32_16x16x32_bf16 v[2:5], v[168:171], v[204:207], v[2:5]
	s_setprio 0
	s_barrier
; #define PG8_STAGE(bufoff, gbase, voff) do { _Pragma("unroll") for (int _i = 0; _i < 2; ++_i) \
;         __builtin_amdgcn_global_load_lds((const unsigned*)((const char*)(gbase) + (voff)[_i]), (LAS unsigned*)(lds + (bufoff) + ldsw + _i * 8192), 16, 0, 0); } while (0)
; #define PG8_LDA(dst, b, h) do { _Pragma("unroll") for (int m = 0; m < 4; ++m) _Pragma("unroll") for (int k = 0; k < 2; ++k) dst[m][k] = *(const LAS bf16x8*)(lds + PG8_SA(b, h) + aoff + m * 2048 + k * 1024); } while (0)
; #define PG8_LDB(dst, b, h) do { _Pragma("unroll") for (int n = 0; n < 2; ++n) _Pragma("unroll") for (int k = 0; k < 2; ++k) dst[n][k] = *(const LAS bf16x8*)(lds + PG8_SB(b, h) + boff + n * 2048 + k * 1024); } while (0)
; #define PG8_MMA(ai, bj, At, Bt) do { __builtin_amdgcn_s_setprio(1); _Pragma("unroll") for (int m = 0; m < 4; ++m) _Pragma("unroll") for (int n = 0; n < 2; ++n) _Pragma("unroll") for (int k = 0; k < 2; ++k) \
;         acc[ai][bj][m][n] = __builtin_amdgcn_mfma_f32_16x16x32_bf16(Bt[n][k], At[m][k], acc[ai][bj][m][n], 0, 0, 0); __builtin_amdgcn_s_setprio(0); } while (0)
; #define PG8_WAIT_V(n) asm volatile("s_waitcnt vmcnt(" #n ")" ::: "memory")
; #define PG8_WAIT_L(n) asm volatile("s_waitcnt lgkmcnt(" #n ")" ::: "memory")
; #define PG8_BAR __builtin_amdgcn_s_barrier()
; #define PG8_SCHED __builtin_amdgcn_sched_barrier(0)
; template <class Epi, class Sched>
; __device__ __forceinline__ void gemm_phase(LAS unsigned char* lds, const int lda, const int ldb, const int K, const Sched& S, const Epi& E, int tid) {
;     ...
;             PG8_LDB(B0, 1, 0); PG8_LDB(B1, 1, 1); PG8_SCHED; PG8_LDA(At, 1, 0); PG8_STAGE(PG8_SA(0, 1), a2 + hA, voffA);
;             PG8_WAIT_V(8); PG8_WAIT_L(0); PG8_BAR; PG8_MMA(0, 0, At, B0); PG8_MMA(0, 1, At, B1); PG8_BAR; PG8_SCHED;
;             PG8_LDA(At, 1, 1); PG8_STAGE(PG8_SB(1, 0), b3, voffB); PG8_STAGE(PG8_SB(1, 1), b3 + hB, voffB); PG8_STAGE(PG8_SA(1, 0), a3, voffA);
;             PG8_WAIT_V(8); PG8_WAIT_L(0); PG8_BAR; PG8_MMA(1, 0, At, B0); PG8_MMA(1, 1, At, B1); PG8_BAR; PG8_SCHED;
;         }
;         if (wr == 0) PG8_BAR;
	s_add_i32 s33, 0, 0x18000
	s_add_i32 s34, 0, 0x1c000
	v_add_u32_e32 v130, s33, v208
	v_add_u32_e32 v168, s34, v208
	ds_read_b128 v[86:89], v130
	ds_read_b128 v[106:109], v130 offset:1024
	ds_read_b128 v[126:129], v130 offset:2048
	ds_read_b128 v[130:133], v130 offset:3072
	ds_read_b128 v[156:159], v168
	ds_read_b128 v[160:163], v168 offset:1024
	ds_read_b128 v[164:167], v168 offset:2048
	ds_read_b128 v[168:171], v168 offset:3072
	s_add_u32 s2, s8, 0x160000
	s_addc_u32 s3, s9, 0
	s_mov_b32 m0, s17
	ds_read_b128 v[172:175], v210 offset:32768
	ds_read_b128 v[176:179], v210 offset:33792
	ds_read_b128 v[180:183], v210 offset:34816
	ds_read_b128 v[184:187], v210 offset:35840
	ds_read_b128 v[188:191], v210 offset:36864
	ds_read_b128 v[192:195], v210 offset:37888
	ds_read_b128 v[200:203], v210 offset:38912
	ds_read_b128 v[204:207], v210 offset:39936
	global_load_lds_dwordx4 v146, s[2:3]
	s_mov_b32 m0, s18
	s_nop 0
	global_load_lds_dwordx4 v148, s[2:3]
	s_waitcnt vmcnt(8)
	s_waitcnt lgkmcnt(0)
	s_barrier
	s_setprio 1
	s_waitcnt lgkmcnt(0)
	v_mfma_f32_16x16x32_bf16 v[142:145], v[86:89], v[172:175], v[142:145]
	v_mfma_f32_16x16x32_bf16 v[102:105], v[126:129], v[172:175], v[102:105]
	v_mfma_f32_16x16x32_bf16 v[138:141], v[86:89], v[180:183], v[138:141]
	v_mfma_f32_16x16x32_bf16 v[98:101], v[126:129], v[180:183], v[98:101]
	v_mfma_f32_16x16x32_bf16 v[134:137], v[86:89], v[188:191], v[134:137]
	v_mfma_f32_16x16x32_bf16 v[94:97], v[126:129], v[188:191], v[94:97]
	v_mfma_f32_16x16x32_bf16 v[122:125], v[86:89], v[200:203], v[122:125]
	v_mfma_f32_16x16x32_bf16 v[90:93], v[126:129], v[200:203], v[90:93]
	v_mfma_f32_16x16x32_bf16 v[142:145], v[106:109], v[176:179], v[142:145]
	v_mfma_f32_16x16x32_bf16 v[102:105], v[130:133], v[176:179], v[102:105]
	v_mfma_f32_16x16x32_bf16 v[138:141], v[106:109], v[184:187], v[138:141]
	v_mfma_f32_16x16x32_bf16 v[98:101], v[130:133], v[184:187], v[98:101]
	v_mfma_f32_16x16x32_bf16 v[134:137], v[106:109], v[192:195], v[134:137]
	v_mfma_f32_16x16x32_bf16 v[94:97], v[130:133], v[192:195], v[94:97]
	v_mfma_f32_16x16x32_bf16 v[122:125], v[106:109], v[204:207], v[122:125]
	v_mfma_f32_16x16x32_bf16 v[90:93], v[130:133], v[204:207], v[90:93]
	s_setprio 0
	s_setprio 1
	v_mfma_f32_16x16x32_bf16 v[66:69], v[156:159], v[172:175], v[66:69]
	v_mfma_f32_16x16x32_bf16 v[34:37], v[164:167], v[172:175], v[34:37]
	v_mfma_f32_16x16x32_bf16 v[58:61], v[156:159], v[180:183], v[58:61]
	v_mfma_f32_16x16x32_bf16 v[26:29], v[164:167], v[180:183], v[26:29]
	v_mfma_f32_16x16x32_bf16 v[54:57], v[156:159], v[188:191], v[54:57]
	v_mfma_f32_16x16x32_bf16 v[22:25], v[164:167], v[188:191], v[22:25]
	v_mfma_f32_16x16x32_bf16 v[50:53], v[156:159], v[200:203], v[50:53]
	v_mfma_f32_16x16x32_bf16 v[18:21], v[164:167], v[200:203], v[18:21]
	v_mfma_f32_16x16x32_bf16 v[66:69], v[160:163], v[176:179], v[66:69]
	v_mfma_f32_16x16x32_bf16 v[34:37], v[168:171], v[176:179], v[34:37]
	v_mfma_f32_16x16x32_bf16 v[58:61], v[160:163], v[184:187], v[58:61]
	v_mfma_f32_16x16x32_bf16 v[26:29], v[168:171], v[184:187], v[26:29]
	v_mfma_f32_16x16x32_bf16 v[54:57], v[160:163], v[192:195], v[54:57]
	v_mfma_f32_16x16x32_bf16 v[22:25], v[168:171], v[192:195], v[22:25]
	v_mfma_f32_16x16x32_bf16 v[50:53], v[160:163], v[204:207], v[50:53]
	v_mfma_f32_16x16x32_bf16 v[18:21], v[168:171], v[204:207], v[18:21]
	s_setprio 0
	s_barrier
	s_add_i32 s2, s33, s14
	s_mov_b32 m0, s2
	ds_read_b128 v[172:175], v210 offset:49152
	ds_read_b128 v[176:179], v210 offset:50176
	ds_read_b128 v[180:183], v210 offset:51200
	ds_read_b128 v[184:187], v210 offset:52224
	ds_read_b128 v[188:191], v210 offset:53248
	ds_read_b128 v[192:195], v210 offset:54272
	ds_read_b128 v[200:203], v210 offset:55296
	ds_read_b128 v[204:207], v210 offset:56320
	global_load_lds_dwordx4 v0, s[98:99]
	s_add_i32 m0, s2, 0x2000
	s_add_u32 s2, s6, 0x160080
	s_addc_u32 s3, s7, 0
	s_add_i32 s6, s34, s14
	global_load_lds_dwordx4 v150, s[98:99]
	s_mov_b32 m0, s6
	s_nop 0
	global_load_lds_dwordx4 v0, s[2:3]
	s_add_i32 m0, s6, 0x2000
	s_nop 0
	global_load_lds_dwordx4 v150, s[2:3]
	s_mov_b32 m0, s19
	s_nop 0
	global_load_lds_dwordx4 v146, s[100:101]
	s_mov_b32 m0, s20
	s_nop 0
	global_load_lds_dwordx4 v148, s[100:101]
	s_waitcnt vmcnt(8)
	s_waitcnt lgkmcnt(0)
	s_barrier
	s_setprio 1
	s_waitcnt lgkmcnt(0)
	v_mfma_f32_16x16x32_bf16 v[118:121], v[86:89], v[172:175], v[118:121]
	v_mfma_f32_16x16x32_bf16 v[78:81], v[126:129], v[172:175], v[78:81]
	v_mfma_f32_16x16x32_bf16 v[114:117], v[86:89], v[180:183], v[114:117]
	v_mfma_f32_16x16x32_bf16 v[74:77], v[126:129], v[180:183], v[74:77]
	v_mfma_f32_16x16x32_bf16 v[110:113], v[86:89], v[188:191], v[110:113]
	v_mfma_f32_16x16x32_bf16 v[70:73], v[126:129], v[188:191], v[70:73]
	v_mfma_f32_16x16x32_bf16 v[82:85], v[86:89], v[200:203], v[82:85]
	v_mfma_f32_16x16x32_bf16 v[62:65], v[126:129], v[200:203], v[62:65]
	v_mfma_f32_16x16x32_bf16 v[118:121], v[106:109], v[176:179], v[118:121]
	v_mfma_f32_16x16x32_bf16 v[78:81], v[130:133], v[176:179], v[78:81]
	v_mfma_f32_16x16x32_bf16 v[114:117], v[106:109], v[184:187], v[114:117]
	v_mfma_f32_16x16x32_bf16 v[74:77], v[130:133], v[184:187], v[74:77]
	v_mfma_f32_16x16x32_bf16 v[110:113], v[106:109], v[192:195], v[110:113]
	v_mfma_f32_16x16x32_bf16 v[70:73], v[130:133], v[192:195], v[70:73]
	v_mfma_f32_16x16x32_bf16 v[106:109], v[106:109], v[204:207], v[82:85]
	v_mfma_f32_16x16x32_bf16 v[62:65], v[130:133], v[204:207], v[62:65]
	s_setprio 0
	s_setprio 1
	v_mfma_f32_16x16x32_bf16 v[46:49], v[156:159], v[172:175], v[46:49]
	v_mfma_f32_16x16x32_bf16 v[14:17], v[164:167], v[172:175], v[14:17]
	v_mfma_f32_16x16x32_bf16 v[42:45], v[156:159], v[180:183], v[42:45]
	v_mfma_f32_16x16x32_bf16 v[10:13], v[164:167], v[180:183], v[10:13]
	v_mfma_f32_16x16x32_bf16 v[38:41], v[156:159], v[188:191], v[38:41]
	v_mfma_f32_16x16x32_bf16 v[6:9], v[164:167], v[188:191], v[6:9]
	v_mfma_f32_16x16x32_bf16 v[30:33], v[156:159], v[200:203], v[30:33]
	v_mfma_f32_16x16x32_bf16 v[2:5], v[164:167], v[200:203], v[2:5]
	v_mfma_f32_16x16x32_bf16 v[46:49], v[160:163], v[176:179], v[46:49]
	v_mfma_f32_16x16x32_bf16 v[14:17], v[168:171], v[176:179], v[14:17]
	v_mfma_f32_16x16x32_bf16 v[42:45], v[160:163], v[184:187], v[42:45]
	v_mfma_f32_16x16x32_bf16 v[10:13], v[168:171], v[184:187], v[10:13]
	v_mfma_f32_16x16x32_bf16 v[38:41], v[160:163], v[192:195], v[38:41]
	v_mfma_f32_16x16x32_bf16 v[6:9], v[168:171], v[192:195], v[6:9]
	v_mfma_f32_16x16x32_bf16 v[30:33], v[160:163], v[204:207], v[30:33]
	v_mfma_f32_16x16x32_bf16 v[2:5], v[168:171], v[204:207], v[2:5]
	s_setprio 0
	s_barrier
	s_add_i32 s29, s29, 2
	s_add_u32 s25, s25, 0x100
	s_addc_u32 s28, s28, 0
	s_cmpk_gt_u32 s29, 0x55
	s_mov_b64 s[2:3], s[4:5]
	s_cbranch_scc0 .LBB0_880
	s_and_b64 vcc, exec, s[46:47]
	s_cbranch_vccz .LBB0_883
	s_barrier
